# sample_gemm K=1024 x6: coalesced global loads staged via wave-private swizzled LDS
# speedup vs baseline: 1.0583x; 1.0583x over previous
; template <class EpiS>
; DI void sample_gemm(LAS unsigned char* lds, const bf16_t* A, const bf16_t* Bt, int nN, int K, const EpiS& E) {
;     const int tid = threadIdx.x, lane = tid & 63, w = __builtin_amdgcn_readfirstlane(tid >> 6), r32 = lane & 31, h = lane >> 5;
;     const int nunits = 16 * nN, kw = K >> 3, nk = kw >> 4;
;     for (int un = (int)blockIdx.x; un < nunits; un += (int)gridDim.x) {
;         const int rb = un & 3, wc = (un >> 2) & 3, pn = un >> 4;
;         const bf16_t* ap = A + (size_t)(MP + rb * 32 + r32) * K + w * kw + h * 8;
;         const bf16_t* b0p = Bt + (size_t)(pn * 256 + wc * 32 + r32) * K + w * kw + h * 8;
;         const bf16_t* b1p = b0p + (size_t)128 * K;
;         f32x16 c0, c1;
; #pragma unroll
;         for (int r = 0; r < 16; ++r) { c0[r] = 0.f; c1[r] = 0.f; }
.LBB0_336:
	s_cmpk_gt_i32 s2, 0x9f
	v_readfirstlane_b32 s4, v1
	s_cbranch_scc1 .LBB0_351
	v_and_b32_e32 v155, 63, v1
	v_lshrrev_b32_e32 v156, 6, v1
	v_and_b32_e32 v156, 7, v156
	v_lshlrev_b32_e32 v156, 13, v156
	v_add_u32_e32 v156, 0x10000, v156
	v_lshrrev_b32_e32 v182, 3, v155
	v_and_b32_e32 v165, 31, v155
	v_sub_u32_e32 v182, v182, v165
	v_lshlrev_b32_e32 v182, 11, v182
	v_and_b32_e32 v165, 7, v155
	v_lshrrev_b32_e32 v183, 5, v155
	v_sub_u32_e32 v165, v165, v183
	v_lshl_add_u32 v182, v165, 4, v182
	v_ashrrev_i32_e32 v183, 31, v182
	v_lshrrev_b32_e32 v194, 4, v155
	v_and_b32_e32 v194, 3, v194
	v_and_b32_e32 v165, 7, v155
	v_xor_b32_e32 v194, v194, v165
	v_lshlrev_b32_e32 v194, 4, v194
	v_lshrrev_b32_e32 v165, 3, v155
	v_lshl_add_u32 v194, v165, 7, v194
	v_add_u32_e32 v194, v156, v194
	v_xor_b32_e32 v195, 64, v194
	v_and_b32_e32 v165, 31, v155
	v_lshl_add_u32 v156, v165, 7, v156
	v_lshrrev_b32_e32 v165, 1, v155
	v_and_b32_e32 v165, 7, v165
	v_lshrrev_b32_e32 v155, 5, v155
	v_add_u32_e32 v244, 0, v155
	v_xor_b32_e32 v244, v244, v165
	v_lshl_add_u32 v244, v244, 4, v156
	v_add_u32_e32 v245, 2, v155
	v_xor_b32_e32 v245, v245, v165
	v_lshl_add_u32 v245, v245, 4, v156
	v_add_u32_e32 v246, 4, v155
	v_xor_b32_e32 v246, v246, v165
	v_lshl_add_u32 v246, v246, 4, v156
	v_add_u32_e32 v193, 6, v155
	v_xor_b32_e32 v193, v193, v165
	v_lshl_add_u32 v193, v193, 4, v156
	s_mov_b32 s80, 0x4000
	s_mov_b32 s81, 0
	s_mov_b32 s82, 0xffff4000
	s_mov_b32 s83, -1
	v_and_b32_e32 v6, 1, v187
	v_lshlrev_b32_e32 v34, 4, v6
	v_mov_b32_e32 v35, 0
	s_lshr_b32 s8, s4, 6
	s_mov_b32 s5, 0
	v_lshl_add_u64 v[2:3], s[34:35], 0, v[34:35]
	s_lshl_b32 s4, s8, 8
	v_lshl_add_u64 v[36:37], v[2:3], 0, s[4:5]
	v_mbcnt_lo_u32_b32 v2, -1, 0
	v_lshl_add_u64 v[4:5], s[26:27], 0, v[34:35]
	v_mbcnt_hi_u32_b32 v2, -1, v2
	v_and_b32_e32 v42, 31, v1
	v_lshl_add_u64 v[38:39], v[4:5], 0, s[4:5]
	v_and_b32_e32 v4, 64, v2
	v_lshlrev_b32_e32 v6, 10, v6
	v_lshlrev_b32_e32 v7, 2, v42
	v_xor_b32_e32 v3, 8, v2
	v_add_u32_e32 v4, 64, v4
	v_add3_u32 v7, 0, v6, v7
	v_and_b32_e32 v6, 0x3f00, v184
	s_lshl_b32 s4, s8, 13
	v_cmp_lt_i32_e32 vcc, v3, v4
	v_add_u32_e32 v8, 0, v6
	v_and_b32_e32 v9, 0xf0, v184
	v_and_b32_e32 v10, 1, v185
	v_and_b32_e32 v6, 28, v186
	v_cndmask_b32_e32 v2, v2, v3, vcc
	v_add_u32_e32 v45, s4, v7
	s_movk_i32 s26, 0xf000
	v_lshrrev_b32_e32 v1, 4, v1
	v_lshlrev_b32_e32 v43, 7, v10
	v_cmp_eq_u32_e64 s[0:1], 0, v10
	v_lshlrev_b32_e32 v44, 2, v2
	s_lshl_b32 s8, s2, 3
	s_lshl_b32 s9, s3, 3
	s_lshl_b32 s33, s2, 5
	s_lshl_b32 s66, s3, 5
	s_mov_b32 s67, 0x40000
	v_add_u32_e32 v46, v8, v9
	v_mov_b32_e32 v47, 0x358637bd
	s_mov_b32 s68, 0x800000
	s_mov_b32 s27, -1
	v_lshlrev_b32_e32 v40, 1, v6
	v_add_u32_e32 v48, 0x800, v45
	v_add_u32_e32 v49, 0x1000, v45
	v_add_u32_e32 v50, 0x1800, v45
	s_mov_b32 s69, s2
	s_branch .LBB0_339

; template <class EpiS>
; DI void sample_gemm(LAS unsigned char* lds, const bf16_t* A, const bf16_t* Bt, int nN, int K, const EpiS& E) {
;     ...
;     for (int un = (int)blockIdx.x; un < nunits; un += (int)gridDim.x) {
;         const int rb = un & 3, wc = (un >> 2) & 3, pn = un >> 4;
;         const bf16_t* ap = A + (size_t)(MP + rb * 32 + r32) * K + w * kw + h * 8;
;         const bf16_t* b0p = Bt + (size_t)(pn * 256 + wc * 32 + r32) * K + w * kw + h * 8;
;         const bf16_t* b1p = b0p + (size_t)128 * K;
;         f32x16 c0, c1;
; #pragma unroll
;         for (int r = 0; r < 16; ++r) { c0[r] = 0.f; c1[r] = 0.f; }
; #pragma unroll 8
;         for (int ks = 0; ks < nk; ++ks) {
;             const bf16x8 a = *(const bf16x8*)(ap + ks * 16), b0 = *(const bf16x8*)(b0p + ks * 16), b1 = *(const bf16x8*)(b1p + ks * 16);
;             c0 = __builtin_amdgcn_mfma_f32_32x32x16_bf16(a, b0, c0, 0, 0, 0);
;             c1 = __builtin_amdgcn_mfma_f32_32x32x16_bf16(a, b1, c1, 0, 0, 0);
;         }
;         __syncthreads();
.LBB0_339:
	s_and_b32 s4, s33, 0x60
	s_or_b32 s50, s4, 0x8000
	v_or_b32_e32 v3, s50, v42
	s_ashr_i32 s71, s69, 4
	s_and_b32 s70, s8, 0x60
	v_lshlrev_b32_e32 v34, 11, v3
	s_lshl_b32 s4, s71, 8
	v_or_b32_e32 v2, s70, v42
	v_lshl_add_u64 v[76:77], v[36:37], 0, v[34:35]
	v_or_b32_e32 v2, s4, v2
	v_ashrrev_i32_e32 v3, 31, v2
	v_lshlrev_b64 v[2:3], 11, v[2:3]
	v_lshl_add_u64 v[78:79], v[38:39], 0, v[2:3]
	v_add_co_u32_e32 v80, vcc, s67, v78
	v_add_u32_e32 v41, s50, v1
	s_nop 0
	v_addc_co_u32_e32 v81, vcc, 0, v79, vcc
	v_lshlrev_b32_e32 v34, 2, v41
	s_cmp_gt_i32 s71, 7
	s_waitcnt vmcnt(6) lgkmcnt(0)
	v_lshl_add_u64 v[158:159], v[76:77], 0, v[182:183]
	v_lshl_add_u64 v[160:161], v[78:79], 0, v[182:183]
	v_lshl_add_u64 v[180:181], v[80:81], 0, v[182:183]
	global_load_dwordx4 v[82:85], v[158:159], off
	v_lshl_add_u64 v[158:159], v[158:159], 0, s[80:81]
	global_load_dwordx4 v[86:89], v[158:159], off
	v_lshl_add_u64 v[158:159], v[158:159], 0, s[80:81]
	global_load_dwordx4 v[90:93], v[158:159], off
	v_lshl_add_u64 v[158:159], v[158:159], 0, s[80:81]
	global_load_dwordx4 v[94:97], v[158:159], off
	v_lshl_add_u64 v[158:159], v[158:159], 0, s[82:83]
	global_load_dwordx4 v[98:101], v[160:161], off
	v_lshl_add_u64 v[160:161], v[160:161], 0, s[80:81]
	global_load_dwordx4 v[102:105], v[160:161], off
	v_lshl_add_u64 v[160:161], v[160:161], 0, s[80:81]
	global_load_dwordx4 v[106:109], v[160:161], off
	v_lshl_add_u64 v[160:161], v[160:161], 0, s[80:81]
	global_load_dwordx4 v[110:113], v[160:161], off
	v_lshl_add_u64 v[160:161], v[160:161], 0, s[82:83]
	global_load_dwordx4 v[132:135], v[180:181], off
	v_lshl_add_u64 v[180:181], v[180:181], 0, s[80:81]
	global_load_dwordx4 v[136:139], v[180:181], off
	v_lshl_add_u64 v[180:181], v[180:181], 0, s[80:81]
	global_load_dwordx4 v[140:143], v[180:181], off
	v_lshl_add_u64 v[180:181], v[180:181], 0, s[80:81]
	global_load_dwordx4 v[144:147], v[180:181], off
	v_lshl_add_u64 v[180:181], v[180:181], 0, s[82:83]
	global_load_dwordx4 v[148:151], v[158:159], off offset:128
	v_lshl_add_u64 v[158:159], v[158:159], 0, s[80:81]
	global_load_dwordx4 v[166:169], v[158:159], off offset:128
	v_lshl_add_u64 v[158:159], v[158:159], 0, s[80:81]
	global_load_dwordx4 v[170:173], v[158:159], off offset:128
	v_lshl_add_u64 v[158:159], v[158:159], 0, s[80:81]
	global_load_dwordx4 v[174:177], v[158:159], off offset:128
	global_load_dwordx4 v[198:201], v[160:161], off offset:128
	v_lshl_add_u64 v[160:161], v[160:161], 0, s[80:81]
	global_load_dwordx4 v[202:205], v[160:161], off offset:128
	v_lshl_add_u64 v[160:161], v[160:161], 0, s[80:81]
	global_load_dwordx4 v[216:219], v[160:161], off offset:128
	v_lshl_add_u64 v[160:161], v[160:161], 0, s[80:81]
	global_load_dwordx4 v[220:223], v[160:161], off offset:128
	global_load_dwordx4 v[224:227], v[180:181], off offset:128
	v_lshl_add_u64 v[180:181], v[180:181], 0, s[80:81]
	global_load_dwordx4 v[228:231], v[180:181], off offset:128
	v_lshl_add_u64 v[180:181], v[180:181], 0, s[80:81]
	global_load_dwordx4 v[232:235], v[180:181], off offset:128
	v_lshl_add_u64 v[180:181], v[180:181], 0, s[80:81]
	global_load_dwordx4 v[236:239], v[180:181], off offset:128
	s_waitcnt vmcnt(16)
	ds_write_b128 v194, v[82:85]
	ds_write_b128 v195, v[86:89] offset:1024
	ds_write_b128 v194, v[90:93] offset:2048
	ds_write_b128 v195, v[94:97] offset:3072
	ds_write_b128 v194, v[98:101] offset:4096
	ds_write_b128 v195, v[102:105] offset:5120
	ds_write_b128 v194, v[106:109] offset:6144
	ds_write_b128 v195, v[110:113] offset:7168
	ds_read_b128 v[82:85], v244
	ds_read_b128 v[86:89], v245
	ds_read_b128 v[90:93], v246
	ds_read_b128 v[94:97], v193
	ds_read_b128 v[98:101], v244 offset:4096
	ds_read_b128 v[102:105], v245 offset:4096
	ds_read_b128 v[106:109], v246 offset:4096
	ds_read_b128 v[110:113], v193 offset:4096
	s_waitcnt lgkmcnt(0)
	v_mfma_f32_32x32x16_bf16 v[2:17], v[82:85], v[98:101], 0
	v_mfma_f32_32x32x16_bf16 v[2:17], v[86:89], v[102:105], v[2:17]
	v_mfma_f32_32x32x16_bf16 v[2:17], v[90:93], v[106:109], v[2:17]
	v_mfma_f32_32x32x16_bf16 v[2:17], v[94:97], v[110:113], v[2:17]
	s_waitcnt vmcnt(12)
	ds_write_b128 v194, v[132:135] offset:4096
	ds_write_b128 v195, v[136:139] offset:5120
	ds_write_b128 v194, v[140:143] offset:6144
	ds_write_b128 v195, v[144:147] offset:7168
	ds_read_b128 v[132:135], v244 offset:4096
	ds_read_b128 v[136:139], v245 offset:4096
	ds_read_b128 v[140:143], v246 offset:4096
	ds_read_b128 v[144:147], v193 offset:4096
	s_waitcnt lgkmcnt(0)
	v_mfma_f32_32x32x16_bf16 v[18:33], v[82:85], v[132:135], 0
	v_mfma_f32_32x32x16_bf16 v[18:33], v[86:89], v[136:139], v[18:33]
	v_mfma_f32_32x32x16_bf16 v[18:33], v[90:93], v[140:143], v[18:33]
	v_mfma_f32_32x32x16_bf16 v[18:33], v[94:97], v[144:147], v[18:33]
	s_waitcnt vmcnt(4)
	ds_write_b128 v194, v[148:151]
	ds_write_b128 v195, v[166:169] offset:1024
	ds_write_b128 v194, v[170:173] offset:2048
	ds_write_b128 v195, v[174:177] offset:3072
	ds_write_b128 v194, v[198:201] offset:4096
	ds_write_b128 v195, v[202:205] offset:5120
	ds_write_b128 v194, v[216:219] offset:6144
	ds_write_b128 v195, v[220:223] offset:7168
	ds_read_b128 v[148:151], v244
	ds_read_b128 v[166:169], v245
	ds_read_b128 v[170:173], v246
	ds_read_b128 v[174:177], v193
	ds_read_b128 v[198:201], v244 offset:4096
	ds_read_b128 v[202:205], v245 offset:4096
	ds_read_b128 v[216:219], v246 offset:4096
	ds_read_b128 v[220:223], v193 offset:4096
	s_waitcnt lgkmcnt(0)
	v_mfma_f32_32x32x16_bf16 v[2:17], v[148:151], v[198:201], v[2:17]
	v_mfma_f32_32x32x16_bf16 v[2:17], v[166:169], v[202:205], v[2:17]
	v_mfma_f32_32x32x16_bf16 v[2:17], v[170:173], v[216:219], v[2:17]
	v_mfma_f32_32x32x16_bf16 v[2:17], v[174:177], v[220:223], v[2:17]
	s_waitcnt vmcnt(0)
	ds_write_b128 v194, v[224:227] offset:4096
	ds_write_b128 v195, v[228:231] offset:5120
	ds_write_b128 v194, v[232:235] offset:6144
	ds_write_b128 v195, v[236:239] offset:7168
	ds_read_b128 v[224:227], v244 offset:4096
	ds_read_b128 v[228:231], v245 offset:4096
	ds_read_b128 v[232:235], v246 offset:4096
	ds_read_b128 v[236:239], v193 offset:4096
	s_waitcnt lgkmcnt(0)
	v_mfma_f32_32x32x16_bf16 v[18:33], v[148:151], v[224:227], v[18:33]
	v_mfma_f32_32x32x16_bf16 v[18:33], v[166:169], v[228:231], v[18:33]
	v_mfma_f32_32x32x16_bf16 v[18:33], v[170:173], v[232:235], v[18:33]
	v_mfma_f32_32x32x16_bf16 v[18:33], v[174:177], v[236:239], v[18:33]
	s_barrier
; #define LAS __attribute__((address_space(3)))
; DI float sigmoidf_(float x) { return __builtin_amdgcn_rcpf(1.0f + __expf(-x)); }
; DI float row_rstd(const float* SS, int row) { return rsqrtf(SS[row] * (1.0f / 1024.0f) + 1e-6f); }
; DI f32x4 shx8(const f32x4 v) { f32x4 o; o[0] = __shfl_xor(v[0], 8); o[1] = __shfl_xor(v[1], 8); o[2] = __shfl_xor(v[2], 8); o[3] = __shfl_xor(v[3], 8); return o; }
; DI u32x2 pk4(const f32x4 a) { return (u32x2){pk2(a[0], a[1]), pk2(a[2], a[3])}; }
;     DI void operator()(const f32x4 vraw, int row, int pn, int wc, int bj, int cl) const {
;         const f32x4 v = vraw * row_rstd(SS, row);
;         const f32x4 o = shx8(v);
;         if (pn < 8) {
;             if (bj == 0) {
;                 f32x4 y = o;
;                 if (pn < 4) {
; #pragma unroll
;                     for (int i = 0; i < 4; ++i) y[i] = sigmoidf_(y[i]);
;                 }
;                 bf16_t* O = (pn < 4) ? A0 : Z0;
;                 *(u32x2*)(O + (size_t)row * MW + (pn & 3) * 128 + wc * 32 + cl) = pk4(v * y);
;             }
;         } else *(u32x2*)(GB0 + (size_t)row * MW + (pn - 8) * 256 + bj * 128 + wc * 32 + cl) = pk4(v);
; template <class EpiS>
; DI void sample_gemm(LAS unsigned char* lds, const bf16_t* A, const bf16_t* Bt, int nN, int K, const EpiS& E) {
;     ...
;         __syncthreads();
;         LAS float* part = (LAS float*)(lds + w * 8192);
; #pragma unroll
;         for (int r = 0; r < 16; ++r) { const int row = (r & 3) + 8 * (r >> 2) + 4 * h; part[row * 64 + r32] = c0[r]; part[row * 64 + 32 + r32] = c1[r]; }
;         __syncthreads();
;         f32x4 v = (f32x4){0.f, 0.f, 0.f, 0.f};
; #pragma unroll
;         for (int ww = 0; ww < 8; ++ww) v += *(const LAS f32x4*)(lds + ww * 8192 + (tid >> 4) * 256 + (tid & 15) * 16);
;         E(v, MP + rb * 32 + (tid >> 4), pn, wc, (tid >> 3) & 1, 4 * (tid & 7));
	s_nop 11
	ds_write2_b32 v45, v2, v18 offset1:32
	ds_write2_b32 v45, v3, v19 offset0:64 offset1:96
	ds_write2_b32 v45, v4, v20 offset0:128 offset1:160
	ds_write2_b32 v45, v5, v21 offset0:192 offset1:224
	ds_write2_b32 v48, v6, v22 offset1:32
	ds_write2_b32 v48, v7, v23 offset0:64 offset1:96
	ds_write2_b32 v48, v8, v24 offset0:128 offset1:160
	ds_write2_b32 v48, v9, v25 offset0:192 offset1:224
	ds_write2_b32 v49, v10, v26 offset1:32
	ds_write2_b32 v49, v11, v27 offset0:64 offset1:96
	ds_write2_b32 v49, v12, v28 offset0:128 offset1:160
	ds_write2_b32 v49, v13, v29 offset0:192 offset1:224
	ds_write2_b32 v50, v14, v30 offset1:32
	ds_write2_b32 v50, v15, v31 offset0:64 offset1:96
	ds_write2_b32 v50, v16, v32 offset0:128 offset1:160
	ds_write2_b32 v50, v17, v33 offset0:192 offset1:224
	s_waitcnt lgkmcnt(0)
	s_barrier
	global_load_dword v34, v34, s[6:7]
	ds_read_b128 v[2:5], v46
	ds_read_b128 v[6:9], v46 offset:8192
	ds_read_b128 v[10:13], v46 offset:16384
	ds_read_b128 v[14:17], v46 offset:24576
	ds_read_b128 v[18:21], v46 offset:32768
	ds_read_b128 v[22:25], v46 offset:40960
	ds_read_b128 v[26:29], v46 offset:49152
	ds_read_b128 v[30:33], v46 offset:57344
	s_waitcnt lgkmcnt(7)
	v_pk_add_f32 v[2:3], v[2:3], 0 op_sel_hi:[1,0]
	v_pk_add_f32 v[4:5], v[4:5], 0 op_sel_hi:[1,0]
	s_waitcnt lgkmcnt(6)
	v_pk_add_f32 v[2:3], v[2:3], v[6:7]
	v_pk_add_f32 v[4:5], v[4:5], v[8:9]
	s_waitcnt lgkmcnt(5)
	v_pk_add_f32 v[2:3], v[2:3], v[10:11]
	v_pk_add_f32 v[4:5], v[4:5], v[12:13]
	s_waitcnt lgkmcnt(4)
	v_pk_add_f32 v[2:3], v[2:3], v[14:15]
	v_pk_add_f32 v[4:5], v[4:5], v[16:17]
	s_waitcnt lgkmcnt(3)
	v_pk_add_f32 v[2:3], v[2:3], v[18:19]
	v_pk_add_f32 v[4:5], v[4:5], v[20:21]
	s_waitcnt lgkmcnt(2)
	v_pk_add_f32 v[2:3], v[2:3], v[22:23]
	v_pk_add_f32 v[4:5], v[4:5], v[24:25]
	s_waitcnt lgkmcnt(1)
	v_pk_add_f32 v[2:3], v[2:3], v[26:27]
	v_pk_add_f32 v[4:5], v[4:5], v[28:29]
	s_waitcnt lgkmcnt(0)
	v_pk_add_f32 v[2:3], v[2:3], v[30:31]
	v_pk_add_f32 v[4:5], v[4:5], v[32:33]
	s_waitcnt vmcnt(0)
	v_fmamk_f32 v6, v34, 0x3a800000, v47
	v_mul_f32_e32 v7, 0x4b800000, v6
	v_cmp_gt_f32_e32 vcc, s68, v6
	s_nop 1
	v_cndmask_b32_e32 v6, v6, v7, vcc
	v_rsq_f32_e32 v6, v6
	s_nop 0
	v_mul_f32_e32 v7, 0x45800000, v6
	v_cndmask_b32_e32 v6, v6, v7, vcc
	v_pk_mul_f32 v[2:3], v[2:3], v[6:7] op_sel_hi:[1,0]
	v_pk_mul_f32 v[4:5], v[4:5], v[6:7] op_sel_hi:[1,0]
	ds_bpermute_b32 v6, v44, v2
	ds_bpermute_b32 v7, v44, v3
	ds_bpermute_b32 v8, v44, v4
	ds_bpermute_b32 v9, v44, v5
	s_cbranch_scc0 .LBB0_342
	v_lshlrev_b32_e32 v34, 10, v41
	v_lshl_add_u64 v[12:13], s[10:11], 0, v[34:35]
	v_lshl_add_u64 v[12:13], s[4:5], 1, v[12:13]
	v_cvt_pk_bf16_f32 v10, v2, v3
	v_cvt_pk_bf16_f32 v11, v4, v5
	v_lshl_add_u64 v[12:13], v[12:13], 0, s[26:27]
	s_mov_b64 s[50:51], -1
	s_cbranch_execz .LBB0_343
	v_mov_b32_e32 v34, v43
	s_and_saveexec_b64 s[62:63], s[50:51]
	s_cbranch_execz .LBB0_338
	s_branch .LBB0_350

; template <class EpiS>
; DI void sample_gemm(LAS unsigned char* lds, const bf16_t* A, const bf16_t* Bt, int nN, int K, const EpiS& E) {
;     const int tid = threadIdx.x, lane = tid & 63, w = __builtin_amdgcn_readfirstlane(tid >> 6), r32 = lane & 31, h = lane >> 5;
;     const int nunits = 16 * nN, kw = K >> 3, nk = kw >> 4;
;     for (int un = (int)blockIdx.x; un < nunits; un += (int)gridDim.x) {
;         const int rb = un & 3, wc = (un >> 2) & 3, pn = un >> 4;
;         const bf16_t* ap = A + (size_t)(MP + rb * 32 + r32) * K + w * kw + h * 8;
;         const bf16_t* b0p = Bt + (size_t)(pn * 256 + wc * 32 + r32) * K + w * kw + h * 8;
;         const bf16_t* b1p = b0p + (size_t)128 * K;
;         f32x16 c0, c1;
; #pragma unroll
;         for (int r = 0; r < 16; ++r) { c0[r] = 0.f; c1[r] = 0.f; }
.LBB0_543:
	s_cmp_gt_i32 s2, 63
	v_readfirstlane_b32 s0, v206
	s_cbranch_scc1 .LBB0_548
	v_and_b32_e32 v155, 63, v206
	v_lshrrev_b32_e32 v156, 6, v206
	v_and_b32_e32 v156, 7, v156
	v_lshlrev_b32_e32 v156, 13, v156
	v_add_u32_e32 v156, 0x10000, v156
	v_lshrrev_b32_e32 v182, 3, v155
	v_and_b32_e32 v165, 31, v155
	v_sub_u32_e32 v182, v182, v165
	v_lshlrev_b32_e32 v182, 11, v182
	v_and_b32_e32 v165, 7, v155
	v_lshrrev_b32_e32 v183, 5, v155
	v_sub_u32_e32 v165, v165, v183
	v_lshl_add_u32 v182, v165, 4, v182
	v_ashrrev_i32_e32 v183, 31, v182
	v_lshrrev_b32_e32 v194, 4, v155
	v_and_b32_e32 v194, 3, v194
	v_and_b32_e32 v165, 7, v155
	v_xor_b32_e32 v194, v194, v165
	v_lshlrev_b32_e32 v194, 4, v194
	v_lshrrev_b32_e32 v165, 3, v155
	v_lshl_add_u32 v194, v165, 7, v194
	v_add_u32_e32 v194, v156, v194
	v_xor_b32_e32 v195, 64, v194
	v_and_b32_e32 v165, 31, v155
	v_lshl_add_u32 v156, v165, 7, v156
	v_lshrrev_b32_e32 v165, 1, v155
	v_and_b32_e32 v165, 7, v165
	v_lshrrev_b32_e32 v155, 5, v155
	v_add_u32_e32 v244, 0, v155
	v_xor_b32_e32 v244, v244, v165
	v_lshl_add_u32 v244, v244, 4, v156
	v_add_u32_e32 v245, 2, v155
	v_xor_b32_e32 v245, v245, v165
	v_lshl_add_u32 v245, v245, 4, v156
	v_add_u32_e32 v246, 4, v155
	v_xor_b32_e32 v246, v246, v165
	v_lshl_add_u32 v246, v246, 4, v156
	v_add_u32_e32 v193, 6, v155
	v_xor_b32_e32 v193, v193, v165
	v_lshl_add_u32 v193, v193, 4, v156
	s_mov_b32 s80, 0x4000
	s_mov_b32 s81, 0
	s_mov_b32 s82, 0xffff4000
	s_mov_b32 s83, -1
	v_and_b32_e32 v6, 1, v210
	v_lshlrev_b32_e32 v34, 4, v6
	v_mov_b32_e32 v35, 0
	s_add_u32 s4, s14, 0xf8000000
	v_lshl_add_u64 v[4:5], s[10:11], 0, v[34:35]
	v_and_b32_e32 v9, 28, v209
	s_movk_i32 s10, 0x80
	s_addc_u32 s5, s15, -1
	v_and_or_b32 v41, v207, s10, v9
	s_lshr_b32 s10, s0, 6
	s_mov_b32 s1, 0
	s_waitcnt lgkmcnt(0)
	v_lshl_add_u64 v[2:3], s[26:27], 0, v[34:35]
	s_lshl_b32 s0, s10, 8
	v_lshl_add_u64 v[36:37], v[2:3], 0, s[0:1]
	v_mbcnt_lo_u32_b32 v2, -1, 0
	v_mbcnt_hi_u32_b32 v2, -1, v2
	v_lshl_add_u64 v[38:39], v[4:5], 0, s[0:1]
	v_and_b32_e32 v4, 64, v2
	v_xor_b32_e32 v3, 1, v2
	v_add_u32_e32 v4, 64, v4
	v_cmp_lt_i32_e64 s[0:1], v3, v4
	v_and_b32_e32 v40, 31, v206
	v_lshlrev_b32_e32 v6, 10, v6
	v_cndmask_b32_e64 v3, v2, v3, s[0:1]
	v_lshlrev_b32_e32 v42, 2, v3
	v_xor_b32_e32 v3, 2, v2
	v_cmp_lt_i32_e64 s[0:1], v3, v4
	v_lshlrev_b32_e32 v7, 2, v40
	v_add3_u32 v6, 0, v6, v7
	v_cndmask_b32_e64 v3, v2, v3, s[0:1]
	v_lshlrev_b32_e32 v43, 2, v3
	v_xor_b32_e32 v3, 4, v2
	v_cmp_lt_i32_e64 s[0:1], v3, v4
	v_and_b32_e32 v7, 0x3f00, v207
	s_lshl_b32 s17, s10, 13
	v_cndmask_b32_e64 v3, v2, v3, s[0:1]
	v_lshlrev_b32_e32 v44, 2, v3
	v_xor_b32_e32 v3, 8, v2
	v_cmp_lt_i32_e64 s[0:1], v3, v4
	v_add_u32_e32 v7, 0, v7
	v_and_b32_e32 v8, 0xf0, v207
	v_cndmask_b32_e64 v2, v2, v3, s[0:1]
	v_add_u32_e32 v46, s17, v6
	v_cmp_eq_u32_e32 vcc, 0, v208
	v_lshlrev_b32_e32 v45, 2, v2
	s_lshl_b32 s10, s2, 3
	s_lshl_b32 s11, s3, 3
	s_lshl_b32 s12, s2, 4
	s_lshl_b32 s13, s3, 4
	s_lshl_b32 s14, s2, 5
	s_lshl_b32 s15, s3, 5
	s_mov_b32 s16, 0x40000
	v_add_u32_e32 v47, v7, v8
	v_add_u32_e32 v48, 0x800, v46
	v_add_u32_e32 v49, 0x1000, v46
	v_add_u32_e32 v50, 0x1800, v46
	s_mov_b32 s17, s2
	s_branch .LBB0_546

; template <class EpiS>
; DI void sample_gemm(LAS unsigned char* lds, const bf16_t* A, const bf16_t* Bt, int nN, int K, const EpiS& E) {
;     ...
;     for (int un = (int)blockIdx.x; un < nunits; un += (int)gridDim.x) {
;         const int rb = un & 3, wc = (un >> 2) & 3, pn = un >> 4;
;         const bf16_t* ap = A + (size_t)(MP + rb * 32 + r32) * K + w * kw + h * 8;
;         const bf16_t* b0p = Bt + (size_t)(pn * 256 + wc * 32 + r32) * K + w * kw + h * 8;
;         const bf16_t* b1p = b0p + (size_t)128 * K;
;         f32x16 c0, c1;
; #pragma unroll
;         for (int r = 0; r < 16; ++r) { c0[r] = 0.f; c1[r] = 0.f; }
; #pragma unroll 8
;         for (int ks = 0; ks < nk; ++ks) {
;             const bf16x8 a = *(const bf16x8*)(ap + ks * 16), b0 = *(const bf16x8*)(b0p + ks * 16), b1 = *(const bf16x8*)(b1p + ks * 16);
;             c0 = __builtin_amdgcn_mfma_f32_32x32x16_bf16(a, b0, c0, 0, 0, 0);
;             c1 = __builtin_amdgcn_mfma_f32_32x32x16_bf16(a, b1, c1, 0, 0, 0);
;         }
;         __syncthreads();
.LBB0_546:
	s_and_b32 s0, s14, 0x60
	s_or_b32 s18, s0, 0x8000
	s_waitcnt lgkmcnt(0)
	v_or_b32_e32 v3, s18, v40
	s_and_b32 s0, s12, 0xffffff00
	s_and_b32 s1, s10, 0x60
	v_lshlrev_b32_e32 v34, 11, v3
	s_or_b32 s19, s0, s1
	v_lshl_add_u64 v[76:77], v[36:37], 0, v[34:35]
	v_or_b32_e32 v2, s19, v40
	v_ashrrev_i32_e32 v3, 31, v2
	v_lshlrev_b64 v[2:3], 11, v[2:3]
	v_lshl_add_u64 v[78:79], v[38:39], 0, v[2:3]
	v_add_co_u32_e64 v80, s[0:1], s16, v78
	v_add_u32_e32 v51, s18, v1
	s_nop 0
	v_addc_co_u32_e64 v81, s[0:1], 0, v79, s[0:1]
	v_lshlrev_b32_e32 v34, 12, v51
	v_or_b32_e32 v60, s19, v41
	v_ashrrev_i32_e32 v61, 31, v60
	v_lshl_add_u64 v[56:57], s[4:5], 0, v[34:35]
	v_lshl_add_u64 v[56:57], v[60:61], 2, v[56:57]
	v_lshlrev_b32_e32 v34, 11, v51
	v_lshl_add_u64 v[158:159], v[76:77], 0, v[182:183]
	v_lshl_add_u64 v[160:161], v[78:79], 0, v[182:183]
	v_lshl_add_u64 v[180:181], v[80:81], 0, v[182:183]
	global_load_dwordx4 v[82:85], v[158:159], off
	v_lshl_add_u64 v[158:159], v[158:159], 0, s[80:81]
	global_load_dwordx4 v[86:89], v[158:159], off
	v_lshl_add_u64 v[158:159], v[158:159], 0, s[80:81]
	global_load_dwordx4 v[90:93], v[158:159], off
	v_lshl_add_u64 v[158:159], v[158:159], 0, s[80:81]
	global_load_dwordx4 v[94:97], v[158:159], off
	v_lshl_add_u64 v[158:159], v[158:159], 0, s[82:83]
	global_load_dwordx4 v[98:101], v[160:161], off
	v_lshl_add_u64 v[160:161], v[160:161], 0, s[80:81]
	global_load_dwordx4 v[102:105], v[160:161], off
	v_lshl_add_u64 v[160:161], v[160:161], 0, s[80:81]
	global_load_dwordx4 v[106:109], v[160:161], off
	v_lshl_add_u64 v[160:161], v[160:161], 0, s[80:81]
	global_load_dwordx4 v[110:113], v[160:161], off
	v_lshl_add_u64 v[160:161], v[160:161], 0, s[82:83]
	global_load_dwordx4 v[132:135], v[180:181], off
	v_lshl_add_u64 v[180:181], v[180:181], 0, s[80:81]
	global_load_dwordx4 v[136:139], v[180:181], off
	v_lshl_add_u64 v[180:181], v[180:181], 0, s[80:81]
	global_load_dwordx4 v[140:143], v[180:181], off
	v_lshl_add_u64 v[180:181], v[180:181], 0, s[80:81]
	global_load_dwordx4 v[144:147], v[180:181], off
	v_lshl_add_u64 v[180:181], v[180:181], 0, s[82:83]
	global_load_dwordx4 v[148:151], v[158:159], off offset:128
	v_lshl_add_u64 v[158:159], v[158:159], 0, s[80:81]
	global_load_dwordx4 v[166:169], v[158:159], off offset:128
	v_lshl_add_u64 v[158:159], v[158:159], 0, s[80:81]
	global_load_dwordx4 v[170:173], v[158:159], off offset:128
	v_lshl_add_u64 v[158:159], v[158:159], 0, s[80:81]
	global_load_dwordx4 v[174:177], v[158:159], off offset:128
	global_load_dwordx4 v[198:201], v[160:161], off offset:128
	v_lshl_add_u64 v[160:161], v[160:161], 0, s[80:81]
	global_load_dwordx4 v[202:205], v[160:161], off offset:128
	v_lshl_add_u64 v[160:161], v[160:161], 0, s[80:81]
	global_load_dwordx4 v[216:219], v[160:161], off offset:128
	v_lshl_add_u64 v[160:161], v[160:161], 0, s[80:81]
	global_load_dwordx4 v[220:223], v[160:161], off offset:128
	global_load_dwordx4 v[224:227], v[180:181], off offset:128
	v_lshl_add_u64 v[180:181], v[180:181], 0, s[80:81]
	global_load_dwordx4 v[228:231], v[180:181], off offset:128
	v_lshl_add_u64 v[180:181], v[180:181], 0, s[80:81]
	global_load_dwordx4 v[232:235], v[180:181], off offset:128
	v_lshl_add_u64 v[180:181], v[180:181], 0, s[80:81]
	global_load_dwordx4 v[236:239], v[180:181], off offset:128
	s_waitcnt vmcnt(16)
	ds_write_b128 v194, v[82:85]
	ds_write_b128 v195, v[86:89] offset:1024
	ds_write_b128 v194, v[90:93] offset:2048
	ds_write_b128 v195, v[94:97] offset:3072
	ds_write_b128 v194, v[98:101] offset:4096
	ds_write_b128 v195, v[102:105] offset:5120
	ds_write_b128 v194, v[106:109] offset:6144
	ds_write_b128 v195, v[110:113] offset:7168
	ds_read_b128 v[82:85], v244
	ds_read_b128 v[86:89], v245
	ds_read_b128 v[90:93], v246
	ds_read_b128 v[94:97], v193
	ds_read_b128 v[98:101], v244 offset:4096
	ds_read_b128 v[102:105], v245 offset:4096
	ds_read_b128 v[106:109], v246 offset:4096
	ds_read_b128 v[110:113], v193 offset:4096
	s_waitcnt lgkmcnt(0)
	v_mfma_f32_32x32x16_bf16 v[2:17], v[82:85], v[98:101], 0
	v_mfma_f32_32x32x16_bf16 v[2:17], v[86:89], v[102:105], v[2:17]
	v_mfma_f32_32x32x16_bf16 v[2:17], v[90:93], v[106:109], v[2:17]
	v_mfma_f32_32x32x16_bf16 v[2:17], v[94:97], v[110:113], v[2:17]
	s_waitcnt vmcnt(12)
	ds_write_b128 v194, v[132:135] offset:4096
	ds_write_b128 v195, v[136:139] offset:5120
	ds_write_b128 v194, v[140:143] offset:6144
	ds_write_b128 v195, v[144:147] offset:7168
	ds_read_b128 v[132:135], v244 offset:4096
	ds_read_b128 v[136:139], v245 offset:4096
	ds_read_b128 v[140:143], v246 offset:4096
	ds_read_b128 v[144:147], v193 offset:4096
	s_waitcnt lgkmcnt(0)
	v_mfma_f32_32x32x16_bf16 v[18:33], v[82:85], v[132:135], 0
	v_mfma_f32_32x32x16_bf16 v[18:33], v[86:89], v[136:139], v[18:33]
	v_mfma_f32_32x32x16_bf16 v[18:33], v[90:93], v[140:143], v[18:33]
	v_mfma_f32_32x32x16_bf16 v[18:33], v[94:97], v[144:147], v[18:33]
	s_waitcnt vmcnt(4)
	ds_write_b128 v194, v[148:151]
	ds_write_b128 v195, v[166:169] offset:1024
	ds_write_b128 v194, v[170:173] offset:2048
	ds_write_b128 v195, v[174:177] offset:3072
	ds_write_b128 v194, v[198:201] offset:4096
	ds_write_b128 v195, v[202:205] offset:5120
	ds_write_b128 v194, v[216:219] offset:6144
	ds_write_b128 v195, v[220:223] offset:7168
	ds_read_b128 v[148:151], v244
	ds_read_b128 v[166:169], v245
	ds_read_b128 v[170:173], v246
	ds_read_b128 v[174:177], v193
	ds_read_b128 v[198:201], v244 offset:4096
	ds_read_b128 v[202:205], v245 offset:4096
	ds_read_b128 v[216:219], v246 offset:4096
	ds_read_b128 v[220:223], v193 offset:4096
	s_waitcnt lgkmcnt(0)
	v_mfma_f32_32x32x16_bf16 v[2:17], v[148:151], v[198:201], v[2:17]
	v_mfma_f32_32x32x16_bf16 v[2:17], v[166:169], v[202:205], v[2:17]
	v_mfma_f32_32x32x16_bf16 v[2:17], v[170:173], v[216:219], v[2:17]
	v_mfma_f32_32x32x16_bf16 v[2:17], v[174:177], v[220:223], v[2:17]
	s_waitcnt vmcnt(0)
	ds_write_b128 v194, v[224:227] offset:4096
	ds_write_b128 v195, v[228:231] offset:5120
	ds_write_b128 v194, v[232:235] offset:6144
	ds_write_b128 v195, v[236:239] offset:7168
	ds_read_b128 v[224:227], v244 offset:4096
	ds_read_b128 v[228:231], v245 offset:4096
	ds_read_b128 v[232:235], v246 offset:4096
	ds_read_b128 v[236:239], v193 offset:4096
	s_waitcnt lgkmcnt(0)
	v_mfma_f32_32x32x16_bf16 v[18:33], v[148:151], v[224:227], v[18:33]
	v_mfma_f32_32x32x16_bf16 v[18:33], v[166:169], v[228:231], v[18:33]
	v_mfma_f32_32x32x16_bf16 v[18:33], v[170:173], v[232:235], v[18:33]
	v_mfma_f32_32x32x16_bf16 v[18:33], v[174:177], v[236:239], v[18:33]
	s_barrier
; #define LAS __attribute__((address_space(3)))
; DI float bflo(unsigned u) { return __uint_as_float(u << 16); }
; DI float bfhi(unsigned u) { return __uint_as_float(u & 0xffff0000u); }
; DI float red16(float v) { v += __shfl_xor(v, 1); v += __shfl_xor(v, 2); v += __shfl_xor(v, 4); v += __shfl_xor(v, 8); return v; }
; DI u32x2 pk4(const f32x4 a) { return (u32x2){pk2(a[0], a[1]), pk2(a[2], a[3])}; }
;     DI void operator()(const f32x4 v, int row, int pn, int wc, int bj, int cl) const {
;         const int col = pn * 256 + bj * 128 + wc * 32 + cl;
;         f32x4 x;
;         if (MODE == 0) x = *(const f32x4*)(xin + (size_t)row * D + col);
;         else { const u32x2 w = *(const u32x2*)(XN + (size_t)row * D + col); x = (f32x4){bflo(w.x), bfhi(w.x), bflo(w.y), bfhi(w.y)}; }
;         x += v;
;         if (MODE == 2) *(f32x4*)(out + (size_t)row * D + col) = x;
;         else {
;             *(u32x2*)(XN + (size_t)row * D + col) = pk4(x);
;             const float ssq = red16((x[0] * x[0] + x[1] * x[1]) + (x[2] * x[2] + x[3] * x[3]));
;             if ((threadIdx.x & 15) == 0) atomicAdd(SS + row, ssq);
;         }
; template <class EpiS>
; DI void sample_gemm(LAS unsigned char* lds, const bf16_t* A, const bf16_t* Bt, int nN, int K, const EpiS& E) {
;     ...
;         __syncthreads();
;         LAS float* part = (LAS float*)(lds + w * 8192);
; #pragma unroll
;         for (int r = 0; r < 16; ++r) { const int row = (r & 3) + 8 * (r >> 2) + 4 * h; part[row * 64 + r32] = c0[r]; part[row * 64 + 32 + r32] = c1[r]; }
;         __syncthreads();
;         f32x4 v = (f32x4){0.f, 0.f, 0.f, 0.f};
; #pragma unroll
;         for (int ww = 0; ww < 8; ++ww) v += *(const LAS f32x4*)(lds + ww * 8192 + (tid >> 4) * 256 + (tid & 15) * 16);
;         E(v, MP + rb * 32 + (tid >> 4), pn, wc, (tid >> 3) & 1, 4 * (tid & 7));
	s_nop 11
	ds_write2_b32 v46, v2, v18 offset1:32
	ds_write2_b32 v46, v3, v19 offset0:64 offset1:96
	ds_write2_b32 v46, v4, v20 offset0:128 offset1:160
	ds_write2_b32 v46, v5, v21 offset0:192 offset1:224
	ds_write2_b32 v48, v6, v22 offset1:32
	ds_write2_b32 v48, v7, v23 offset0:64 offset1:96
	ds_write2_b32 v48, v8, v24 offset0:128 offset1:160
	ds_write2_b32 v48, v9, v25 offset0:192 offset1:224
	ds_write2_b32 v49, v10, v26 offset1:32
	ds_write2_b32 v49, v11, v27 offset0:64 offset1:96
	ds_write2_b32 v49, v12, v28 offset0:128 offset1:160
	ds_write2_b32 v49, v13, v29 offset0:192 offset1:224
	ds_write2_b32 v50, v14, v30 offset1:32
	ds_write2_b32 v50, v15, v31 offset0:64 offset1:96
	ds_write2_b32 v50, v16, v32 offset0:128 offset1:160
	ds_write2_b32 v50, v17, v33 offset0:192 offset1:224
	s_waitcnt lgkmcnt(0)
	s_barrier
	global_load_dwordx4 v[2:5], v[56:57], off
	ds_read_b128 v[6:9], v47
	ds_read_b128 v[10:13], v47 offset:8192
	ds_read_b128 v[14:17], v47 offset:16384
	ds_read_b128 v[18:21], v47 offset:24576
	ds_read_b128 v[22:25], v47 offset:32768
	ds_read_b128 v[26:29], v47 offset:40960
	ds_read_b128 v[30:33], v47 offset:49152
	ds_read_b128 v[52:55], v47 offset:57344
	s_waitcnt lgkmcnt(7)
	v_pk_add_f32 v[8:9], v[8:9], 0 op_sel_hi:[1,0]
	v_pk_add_f32 v[6:7], v[6:7], 0 op_sel_hi:[1,0]
	s_waitcnt lgkmcnt(6)
	v_pk_add_f32 v[8:9], v[8:9], v[12:13]
	v_pk_add_f32 v[6:7], v[6:7], v[10:11]
	s_waitcnt lgkmcnt(5)
	v_pk_add_f32 v[8:9], v[8:9], v[16:17]
	v_pk_add_f32 v[6:7], v[6:7], v[14:15]
	s_waitcnt lgkmcnt(4)
	v_pk_add_f32 v[8:9], v[8:9], v[20:21]
	v_pk_add_f32 v[6:7], v[6:7], v[18:19]
	s_waitcnt lgkmcnt(3)
	v_pk_add_f32 v[8:9], v[8:9], v[24:25]
	v_pk_add_f32 v[6:7], v[6:7], v[22:23]
	s_waitcnt lgkmcnt(2)
	v_pk_add_f32 v[8:9], v[8:9], v[28:29]
	v_pk_add_f32 v[6:7], v[6:7], v[26:27]
	s_waitcnt lgkmcnt(1)
	v_pk_add_f32 v[8:9], v[8:9], v[32:33]
	v_pk_add_f32 v[6:7], v[6:7], v[30:31]
	s_waitcnt lgkmcnt(0)
	v_pk_add_f32 v[8:9], v[8:9], v[54:55]
	v_pk_add_f32 v[6:7], v[6:7], v[52:53]
	s_waitcnt vmcnt(0)
	v_pk_add_f32 v[4:5], v[8:9], v[4:5]
	v_pk_add_f32 v[2:3], v[6:7], v[2:3]
	v_mul_f32_e32 v7, v5, v5
	v_mul_f32_e32 v6, v3, v3
	v_fmac_f32_e32 v6, v2, v2
	v_fmac_f32_e32 v7, v4, v4
	v_add_f32_e32 v6, v6, v7
	ds_bpermute_b32 v7, v42, v6
	s_waitcnt lgkmcnt(0)
	v_add_f32_e32 v6, v6, v7
	ds_bpermute_b32 v7, v43, v6
	s_waitcnt lgkmcnt(0)
	v_add_f32_e32 v8, v6, v7
	ds_bpermute_b32 v9, v44, v8
	v_cvt_pk_bf16_f32 v6, v2, v3
	v_cvt_pk_bf16_f32 v7, v4, v5
	v_lshl_add_u64 v[4:5], s[34:35], 0, v[34:35]
	v_lshl_add_u64 v[4:5], v[60:61], 1, v[4:5]
	s_waitcnt lgkmcnt(0)
	v_add_f32_e32 v2, v8, v9
	ds_bpermute_b32 v3, v45, v2
	global_store_dwordx2 v[4:5], v[6:7], off
	s_and_saveexec_b64 s[0:1], vcc
	s_cbranch_execz .LBB0_545
	v_lshlrev_b32_e32 v4, 2, v51
	s_waitcnt lgkmcnt(0)
	v_add_f32_e32 v2, v2, v3
	global_atomic_add_f32 v4, v2, s[8:9]
	s_branch .LBB0_545

; template <class EpiS>
; DI void sample_gemm(LAS unsigned char* lds, const bf16_t* A, const bf16_t* Bt, int nN, int K, const EpiS& E) {
;     const int tid = threadIdx.x, lane = tid & 63, w = __builtin_amdgcn_readfirstlane(tid >> 6), r32 = lane & 31, h = lane >> 5;
;     const int nunits = 16 * nN, kw = K >> 3, nk = kw >> 4;
;     for (int un = (int)blockIdx.x; un < nunits; un += (int)gridDim.x) {
;         const int rb = un & 3, wc = (un >> 2) & 3, pn = un >> 4;
;         const bf16_t* ap = A + (size_t)(MP + rb * 32 + r32) * K + w * kw + h * 8;
;         const bf16_t* b0p = Bt + (size_t)(pn * 256 + wc * 32 + r32) * K + w * kw + h * 8;
;         const bf16_t* b1p = b0p + (size_t)128 * K;
;         f32x16 c0, c1;
; #pragma unroll
;         for (int r = 0; r < 16; ++r) { c0[r] = 0.f; c1[r] = 0.f; }
.LBB0_616:
	s_cmpk_gt_i32 s2, 0x15f
	v_readfirstlane_b32 s0, v162
	s_cbranch_scc1 .LBB0_621
	v_and_b32_e32 v155, 63, v162
	v_lshrrev_b32_e32 v156, 6, v162
	v_and_b32_e32 v156, 7, v156
	v_lshlrev_b32_e32 v156, 13, v156
	v_add_u32_e32 v156, 0x10000, v156
	v_lshrrev_b32_e32 v182, 3, v155
	v_and_b32_e32 v165, 31, v155
	v_sub_u32_e32 v182, v182, v165
	v_lshlrev_b32_e32 v182, 11, v182
	v_and_b32_e32 v165, 7, v155
	v_lshrrev_b32_e32 v183, 5, v155
	v_sub_u32_e32 v165, v165, v183
	v_lshl_add_u32 v182, v165, 4, v182
	v_ashrrev_i32_e32 v183, 31, v182
	v_lshrrev_b32_e32 v194, 4, v155
	v_and_b32_e32 v194, 3, v194
	v_and_b32_e32 v165, 7, v155
	v_xor_b32_e32 v194, v194, v165
	v_lshlrev_b32_e32 v194, 4, v194
	v_lshrrev_b32_e32 v165, 3, v155
	v_lshl_add_u32 v194, v165, 7, v194
	v_add_u32_e32 v194, v156, v194
	v_xor_b32_e32 v195, 64, v194
	v_and_b32_e32 v165, 31, v155
	v_lshl_add_u32 v156, v165, 7, v156
	v_lshrrev_b32_e32 v165, 1, v155
	v_and_b32_e32 v165, 7, v165
	v_lshrrev_b32_e32 v155, 5, v155
	v_add_u32_e32 v244, 0, v155
	v_xor_b32_e32 v244, v244, v165
	v_lshl_add_u32 v244, v244, 4, v156
	v_add_u32_e32 v245, 2, v155
	v_xor_b32_e32 v245, v245, v165
	v_lshl_add_u32 v245, v245, 4, v156
	v_add_u32_e32 v246, 4, v155
	v_xor_b32_e32 v246, v246, v165
	v_lshl_add_u32 v246, v246, 4, v156
	v_add_u32_e32 v193, 6, v155
	v_xor_b32_e32 v193, v193, v165
	v_lshl_add_u32 v193, v193, 4, v156
	s_mov_b32 s80, 0x4000
	s_mov_b32 s81, 0
	s_mov_b32 s82, 0xffff4000
	s_mov_b32 s83, -1
	v_and_b32_e32 v6, 1, v1
	v_lshlrev_b32_e32 v34, 4, v6
	v_mov_b32_e32 v35, 0
	s_lshr_b32 s0, s0, 6
	s_mov_b32 s5, 0
	v_lshl_add_u64 v[2:3], s[34:35], 0, v[34:35]
	s_lshl_b32 s4, s0, 8
	v_lshl_add_u64 v[36:37], v[2:3], 0, s[4:5]
	v_mbcnt_lo_u32_b32 v2, -1, 0
	v_and_b32_e32 v42, 31, v162
	v_lshl_add_u64 v[4:5], s[52:53], 0, v[34:35]
	v_mbcnt_hi_u32_b32 v2, -1, v2
	v_lshlrev_b32_e32 v6, 10, v6
	v_lshlrev_b32_e32 v7, 2, v42
	v_lshl_add_u64 v[38:39], v[4:5], 0, s[4:5]
	v_and_b32_e32 v4, 64, v2
	v_add3_u32 v7, 0, v6, v7
	v_and_b32_e32 v6, 0x3f00, v164
	v_xor_b32_e32 v3, 8, v2
	v_add_u32_e32 v4, 64, v4
	v_add_u32_e32 v8, 0, v6
	v_and_b32_e32 v6, 8, v162
	s_lshl_b32 s4, s0, 13
	v_cmp_lt_i32_e64 s[0:1], v3, v4
	v_and_b32_e32 v9, 0xf0, v164
	v_cmp_eq_u32_e32 vcc, 0, v6
	v_and_b32_e32 v6, 28, v163
	v_cndmask_b32_e64 v2, v2, v3, s[0:1]
	v_add_u32_e32 v45, s4, v7
	v_lshrrev_b32_e32 v43, 4, v162
	v_lshlrev_b32_e32 v44, 2, v2
	s_lshl_b32 s8, s2, 3
	s_lshl_b32 s9, s3, 3
	s_lshl_b32 s10, s2, 5
	s_lshl_b32 s11, s3, 5
	s_mov_b32 s12, 0x40000
	v_add_u32_e32 v46, v8, v9
	v_mov_b32_e32 v47, 0x358637bd
	s_mov_b32 s13, 0x800000
	v_lshlrev_b32_e32 v40, 1, v6
	v_add_u32_e32 v48, 0x800, v45
	v_add_u32_e32 v49, 0x1000, v45
	v_add_u32_e32 v50, 0x1800, v45
	s_mov_b32 s14, s2
	s_branch .LBB0_619

; template <class EpiS>
; DI void sample_gemm(LAS unsigned char* lds, const bf16_t* A, const bf16_t* Bt, int nN, int K, const EpiS& E) {
;     ...
;     for (int un = (int)blockIdx.x; un < nunits; un += (int)gridDim.x) {
;         const int rb = un & 3, wc = (un >> 2) & 3, pn = un >> 4;
;         const bf16_t* ap = A + (size_t)(MP + rb * 32 + r32) * K + w * kw + h * 8;
;         const bf16_t* b0p = Bt + (size_t)(pn * 256 + wc * 32 + r32) * K + w * kw + h * 8;
;         const bf16_t* b1p = b0p + (size_t)128 * K;
;         f32x16 c0, c1;
; #pragma unroll
;         for (int r = 0; r < 16; ++r) { c0[r] = 0.f; c1[r] = 0.f; }
; #pragma unroll 8
;         for (int ks = 0; ks < nk; ++ks) {
;             const bf16x8 a = *(const bf16x8*)(ap + ks * 16), b0 = *(const bf16x8*)(b0p + ks * 16), b1 = *(const bf16x8*)(b1p + ks * 16);
;             c0 = __builtin_amdgcn_mfma_f32_32x32x16_bf16(a, b0, c0, 0, 0, 0);
;             c1 = __builtin_amdgcn_mfma_f32_32x32x16_bf16(a, b1, c1, 0, 0, 0);
;         }
;         __syncthreads();
.LBB0_619:
	s_and_b32 s16, s10, 0x60
	s_bitset1_b32 s16, 15
	s_ashr_i32 s4, s14, 4
	s_waitcnt lgkmcnt(2)
	v_or_b32_e32 v3, s16, v42
	s_lshl_b32 s0, s4, 8
	s_and_b32 s15, s8, 0x60
	v_lshlrev_b32_e32 v34, 11, v3
	s_or_b32 s0, s0, s15
	v_lshl_add_u64 v[76:77], v[36:37], 0, v[34:35]
	v_or_b32_e32 v2, s0, v42
	v_ashrrev_i32_e32 v3, 31, v2
	v_lshlrev_b64 v[2:3], 11, v[2:3]
	v_lshl_add_u64 v[78:79], v[38:39], 0, v[2:3]
	s_waitcnt lgkmcnt(0)
	v_add_co_u32_e64 v80, s[0:1], s12, v78
	v_addc_co_u32_e64 v81, s[0:1], 0, v79, s[0:1]
	v_lshl_add_u64 v[158:159], v[76:77], 0, v[182:183]
	v_lshl_add_u64 v[160:161], v[78:79], 0, v[182:183]
	v_lshl_add_u64 v[180:181], v[80:81], 0, v[182:183]
	global_load_dwordx4 v[82:85], v[158:159], off
	v_lshl_add_u64 v[158:159], v[158:159], 0, s[80:81]
	global_load_dwordx4 v[86:89], v[158:159], off
	v_lshl_add_u64 v[158:159], v[158:159], 0, s[80:81]
	global_load_dwordx4 v[90:93], v[158:159], off
	v_lshl_add_u64 v[158:159], v[158:159], 0, s[80:81]
	global_load_dwordx4 v[94:97], v[158:159], off
	v_lshl_add_u64 v[158:159], v[158:159], 0, s[82:83]
	global_load_dwordx4 v[98:101], v[160:161], off
	v_lshl_add_u64 v[160:161], v[160:161], 0, s[80:81]
	global_load_dwordx4 v[102:105], v[160:161], off
	v_lshl_add_u64 v[160:161], v[160:161], 0, s[80:81]
	global_load_dwordx4 v[106:109], v[160:161], off
	v_lshl_add_u64 v[160:161], v[160:161], 0, s[80:81]
	global_load_dwordx4 v[110:113], v[160:161], off
	v_lshl_add_u64 v[160:161], v[160:161], 0, s[82:83]
	global_load_dwordx4 v[132:135], v[180:181], off
	v_lshl_add_u64 v[180:181], v[180:181], 0, s[80:81]
	global_load_dwordx4 v[136:139], v[180:181], off
	v_lshl_add_u64 v[180:181], v[180:181], 0, s[80:81]
	global_load_dwordx4 v[140:143], v[180:181], off
	v_lshl_add_u64 v[180:181], v[180:181], 0, s[80:81]
	global_load_dwordx4 v[144:147], v[180:181], off
	v_lshl_add_u64 v[180:181], v[180:181], 0, s[82:83]
	global_load_dwordx4 v[148:151], v[158:159], off offset:128
	v_lshl_add_u64 v[158:159], v[158:159], 0, s[80:81]
	global_load_dwordx4 v[166:169], v[158:159], off offset:128
	v_lshl_add_u64 v[158:159], v[158:159], 0, s[80:81]
	global_load_dwordx4 v[170:173], v[158:159], off offset:128
	v_lshl_add_u64 v[158:159], v[158:159], 0, s[80:81]
	global_load_dwordx4 v[174:177], v[158:159], off offset:128
	global_load_dwordx4 v[198:201], v[160:161], off offset:128
	v_lshl_add_u64 v[160:161], v[160:161], 0, s[80:81]
	global_load_dwordx4 v[202:205], v[160:161], off offset:128
	v_lshl_add_u64 v[160:161], v[160:161], 0, s[80:81]
	global_load_dwordx4 v[216:219], v[160:161], off offset:128
	v_lshl_add_u64 v[160:161], v[160:161], 0, s[80:81]
	global_load_dwordx4 v[220:223], v[160:161], off offset:128
	global_load_dwordx4 v[224:227], v[180:181], off offset:128
	v_lshl_add_u64 v[180:181], v[180:181], 0, s[80:81]
	global_load_dwordx4 v[228:231], v[180:181], off offset:128
	v_lshl_add_u64 v[180:181], v[180:181], 0, s[80:81]
	global_load_dwordx4 v[232:235], v[180:181], off offset:128
	v_lshl_add_u64 v[180:181], v[180:181], 0, s[80:81]
	global_load_dwordx4 v[236:239], v[180:181], off offset:128
	s_waitcnt vmcnt(16)
	ds_write_b128 v194, v[82:85]
	ds_write_b128 v195, v[86:89] offset:1024
	ds_write_b128 v194, v[90:93] offset:2048
	ds_write_b128 v195, v[94:97] offset:3072
	ds_write_b128 v194, v[98:101] offset:4096
	ds_write_b128 v195, v[102:105] offset:5120
	ds_write_b128 v194, v[106:109] offset:6144
	ds_write_b128 v195, v[110:113] offset:7168
	ds_read_b128 v[82:85], v244
	ds_read_b128 v[86:89], v245
	ds_read_b128 v[90:93], v246
	ds_read_b128 v[94:97], v193
	ds_read_b128 v[98:101], v244 offset:4096
	ds_read_b128 v[102:105], v245 offset:4096
	ds_read_b128 v[106:109], v246 offset:4096
	ds_read_b128 v[110:113], v193 offset:4096
	s_waitcnt lgkmcnt(0)
	v_mfma_f32_32x32x16_bf16 v[2:17], v[82:85], v[98:101], 0
	v_mfma_f32_32x32x16_bf16 v[2:17], v[86:89], v[102:105], v[2:17]
	v_mfma_f32_32x32x16_bf16 v[2:17], v[90:93], v[106:109], v[2:17]
	v_mfma_f32_32x32x16_bf16 v[2:17], v[94:97], v[110:113], v[2:17]
	s_waitcnt vmcnt(12)
	ds_write_b128 v194, v[132:135] offset:4096
	ds_write_b128 v195, v[136:139] offset:5120
	ds_write_b128 v194, v[140:143] offset:6144
	ds_write_b128 v195, v[144:147] offset:7168
	ds_read_b128 v[132:135], v244 offset:4096
	ds_read_b128 v[136:139], v245 offset:4096
	ds_read_b128 v[140:143], v246 offset:4096
	ds_read_b128 v[144:147], v193 offset:4096
	s_waitcnt lgkmcnt(0)
	v_mfma_f32_32x32x16_bf16 v[18:33], v[82:85], v[132:135], 0
	v_mfma_f32_32x32x16_bf16 v[18:33], v[86:89], v[136:139], v[18:33]
	v_mfma_f32_32x32x16_bf16 v[18:33], v[90:93], v[140:143], v[18:33]
	v_mfma_f32_32x32x16_bf16 v[18:33], v[94:97], v[144:147], v[18:33]
	s_waitcnt vmcnt(4)
	ds_write_b128 v194, v[148:151]
	ds_write_b128 v195, v[166:169] offset:1024
	ds_write_b128 v194, v[170:173] offset:2048
	ds_write_b128 v195, v[174:177] offset:3072
	ds_write_b128 v194, v[198:201] offset:4096
	ds_write_b128 v195, v[202:205] offset:5120
	ds_write_b128 v194, v[216:219] offset:6144
	ds_write_b128 v195, v[220:223] offset:7168
	ds_read_b128 v[148:151], v244
	ds_read_b128 v[166:169], v245
	ds_read_b128 v[170:173], v246
	ds_read_b128 v[174:177], v193
	ds_read_b128 v[198:201], v244 offset:4096
	ds_read_b128 v[202:205], v245 offset:4096
	ds_read_b128 v[216:219], v246 offset:4096
	ds_read_b128 v[220:223], v193 offset:4096
	s_waitcnt lgkmcnt(0)
	v_mfma_f32_32x32x16_bf16 v[2:17], v[148:151], v[198:201], v[2:17]
	v_mfma_f32_32x32x16_bf16 v[2:17], v[166:169], v[202:205], v[2:17]
	v_mfma_f32_32x32x16_bf16 v[2:17], v[170:173], v[216:219], v[2:17]
	v_mfma_f32_32x32x16_bf16 v[2:17], v[174:177], v[220:223], v[2:17]
	s_waitcnt vmcnt(0)
	ds_write_b128 v194, v[224:227] offset:4096
	ds_write_b128 v195, v[228:231] offset:5120
	ds_write_b128 v194, v[232:235] offset:6144
	ds_write_b128 v195, v[236:239] offset:7168
	ds_read_b128 v[224:227], v244 offset:4096
	ds_read_b128 v[228:231], v245 offset:4096
	ds_read_b128 v[232:235], v246 offset:4096
	ds_read_b128 v[236:239], v193 offset:4096
	s_waitcnt lgkmcnt(0)
	v_mfma_f32_32x32x16_bf16 v[18:33], v[148:151], v[224:227], v[18:33]
	v_mfma_f32_32x32x16_bf16 v[18:33], v[166:169], v[228:231], v[18:33]
	v_mfma_f32_32x32x16_bf16 v[18:33], v[170:173], v[232:235], v[18:33]
	v_mfma_f32_32x32x16_bf16 v[18:33], v[174:177], v[236:239], v[18:33]
	s_barrier
; #define LAS __attribute__((address_space(3)))
; DI float sigmoidf_(float x) { return __builtin_amdgcn_rcpf(1.0f + __expf(-x)); }
; DI float row_rstd(const float* SS, int row) { return rsqrtf(SS[row] * (1.0f / 1024.0f) + 1e-6f); }
; DI f32x4 shx8(const f32x4 v) { f32x4 o; o[0] = __shfl_xor(v[0], 8); o[1] = __shfl_xor(v[1], 8); o[2] = __shfl_xor(v[2], 8); o[3] = __shfl_xor(v[3], 8); return o; }
; DI u32x2 pk4(const f32x4 a) { return (u32x2){pk2(a[0], a[1]), pk2(a[2], a[3])}; }
;     DI void operator()(const f32x4 v, int row, int pn, int wc, int bj, int cl) const {
;         const float rs = row_rstd(SS, row);
;         const f32x4 o = shx8(v);
;         if (bj == 0) {
;             f32x4 hv;
; #pragma unroll
;             for (int i = 0; i < 4; ++i) { const float g0 = v[i] * rs; hv[i] = g0 * sigmoidf_(g0) * (o[i] * rs); }
;             *(u32x2*)(HID + (size_t)row * FH + pn * 128 + wc * 32 + cl) = pk4(hv);
;         }
; template <class EpiS>
; DI void sample_gemm(LAS unsigned char* lds, const bf16_t* A, const bf16_t* Bt, int nN, int K, const EpiS& E) {
;     ...
;         __syncthreads();
;         LAS float* part = (LAS float*)(lds + w * 8192);
; #pragma unroll
;         for (int r = 0; r < 16; ++r) { const int row = (r & 3) + 8 * (r >> 2) + 4 * h; part[row * 64 + r32] = c0[r]; part[row * 64 + 32 + r32] = c1[r]; }
;         __syncthreads();
;         f32x4 v = (f32x4){0.f, 0.f, 0.f, 0.f};
; #pragma unroll
;         for (int ww = 0; ww < 8; ++ww) v += *(const LAS f32x4*)(lds + ww * 8192 + (tid >> 4) * 256 + (tid & 15) * 16);
;         E(v, MP + rb * 32 + (tid >> 4), pn, wc, (tid >> 3) & 1, 4 * (tid & 7));
	s_nop 11
	ds_write2_b32 v45, v2, v18 offset1:32
	ds_write2_b32 v45, v3, v19 offset0:64 offset1:96
	ds_write2_b32 v45, v4, v20 offset0:128 offset1:160
	ds_write2_b32 v45, v5, v21 offset0:192 offset1:224
	ds_write2_b32 v48, v6, v22 offset1:32
	ds_write2_b32 v48, v7, v23 offset0:64 offset1:96
	ds_write2_b32 v48, v8, v24 offset0:128 offset1:160
	ds_write2_b32 v48, v9, v25 offset0:192 offset1:224
	ds_write2_b32 v49, v10, v26 offset1:32
	ds_write2_b32 v49, v11, v27 offset0:64 offset1:96
	ds_write2_b32 v49, v12, v28 offset0:128 offset1:160
	ds_write2_b32 v49, v13, v29 offset0:192 offset1:224
	ds_write2_b32 v50, v14, v30 offset1:32
	ds_write2_b32 v50, v15, v31 offset0:64 offset1:96
	ds_write2_b32 v50, v16, v32 offset0:128 offset1:160
	ds_write2_b32 v50, v17, v33 offset0:192 offset1:224
	s_waitcnt lgkmcnt(0)
	s_barrier
	ds_read_b128 v[2:5], v46
	ds_read_b128 v[6:9], v46 offset:8192
	ds_read_b128 v[10:13], v46 offset:16384
	ds_read_b128 v[14:17], v46 offset:24576
	ds_read_b128 v[18:21], v46 offset:32768
	ds_read_b128 v[22:25], v46 offset:40960
	ds_read_b128 v[26:29], v46 offset:49152
	ds_read_b128 v[30:33], v46 offset:57344
	s_waitcnt lgkmcnt(7)
	v_pk_add_f32 v[4:5], v[4:5], 0 op_sel_hi:[1,0]
	v_pk_add_f32 v[2:3], v[2:3], 0 op_sel_hi:[1,0]
	s_waitcnt lgkmcnt(6)
	v_pk_add_f32 v[4:5], v[4:5], v[8:9]
	v_pk_add_f32 v[2:3], v[2:3], v[6:7]
	s_waitcnt lgkmcnt(5)
	v_pk_add_f32 v[4:5], v[4:5], v[12:13]
	v_pk_add_f32 v[2:3], v[2:3], v[10:11]
	s_waitcnt lgkmcnt(4)
	v_pk_add_f32 v[4:5], v[4:5], v[16:17]
	v_pk_add_f32 v[2:3], v[2:3], v[14:15]
	s_waitcnt lgkmcnt(3)
	v_pk_add_f32 v[4:5], v[4:5], v[20:21]
	v_pk_add_f32 v[2:3], v[2:3], v[18:19]
	s_waitcnt lgkmcnt(2)
	v_pk_add_f32 v[4:5], v[4:5], v[24:25]
	v_pk_add_f32 v[2:3], v[2:3], v[22:23]
	s_waitcnt lgkmcnt(1)
	v_pk_add_f32 v[4:5], v[4:5], v[28:29]
	v_pk_add_f32 v[2:3], v[2:3], v[26:27]
	s_waitcnt lgkmcnt(0)
	v_pk_add_f32 v[6:7], v[4:5], v[32:33]
	v_pk_add_f32 v[8:9], v[2:3], v[30:31]
	ds_bpermute_b32 v2, v44, v8
	ds_bpermute_b32 v3, v44, v9
	ds_bpermute_b32 v4, v44, v6
	ds_bpermute_b32 v5, v44, v7
	s_and_saveexec_b64 s[6:7], vcc
	s_cbranch_execz .LBB0_618
	v_add_u32_e32 v10, s16, v43
	v_lshlrev_b32_e32 v11, 2, v10
	global_load_dword v11, v11, s[50:51]
	v_mul_u32_u24_e32 v10, 0xb00, v10
	v_lshlrev_b32_e32 v34, 1, v10
	s_lshl_b32 s16, s4, 7
	s_ashr_i32 s17, s16, 31
	s_lshl_b32 s4, s15, 1
	v_mov_b32_e32 v41, v35
	s_waitcnt vmcnt(0)
	v_fmamk_f32 v10, v11, 0x3a800000, v47
	v_mul_f32_e32 v11, 0x4b800000, v10
	v_cmp_gt_f32_e64 s[0:1], s13, v10
	s_nop 1
	v_cndmask_b32_e64 v10, v10, v11, s[0:1]
	v_rsq_f32_e32 v12, v10
	v_lshl_add_u64 v[10:11], s[24:25], 0, v[34:35]
	v_lshl_add_u64 v[10:11], s[16:17], 1, v[10:11]
	v_lshl_add_u64 v[10:11], v[10:11], 0, s[4:5]
	v_mul_f32_e32 v13, 0x45800000, v12
	v_cndmask_b32_e64 v12, v12, v13, s[0:1]
	v_pk_mul_f32 v[8:9], v[8:9], v[12:13] op_sel_hi:[1,0]
	v_pk_mul_f32 v[6:7], v[6:7], v[12:13] op_sel_hi:[1,0]
	v_mul_f32_e32 v13, 0xbfb8aa3b, v8
	v_mul_f32_e32 v14, 0xbfb8aa3b, v9
	v_mul_f32_e32 v15, 0xbfb8aa3b, v6
	v_mul_f32_e32 v16, 0xbfb8aa3b, v7
	v_exp_f32_e32 v13, v13
	v_exp_f32_e32 v14, v14
	v_exp_f32_e32 v15, v15
	v_exp_f32_e32 v16, v16
	v_add_f32_e32 v13, 1.0, v13
	v_add_f32_e32 v17, 1.0, v14
	v_add_f32_e32 v18, 1.0, v15
	v_add_f32_e32 v19, 1.0, v16
	v_rcp_f32_e32 v14, v13
	v_rcp_f32_e32 v15, v17
	v_rcp_f32_e32 v16, v18
	v_rcp_f32_e32 v17, v19
	s_waitcnt lgkmcnt(2)
	v_pk_mul_f32 v[2:3], v[12:13], v[2:3] op_sel_hi:[0,1]
	s_waitcnt lgkmcnt(0)
	v_pk_mul_f32 v[4:5], v[12:13], v[4:5] op_sel_hi:[0,1]
	v_pk_mul_f32 v[8:9], v[8:9], v[14:15]
	v_pk_mul_f32 v[6:7], v[6:7], v[16:17]
	v_pk_mul_f32 v[2:3], v[2:3], v[8:9]
	v_pk_mul_f32 v[4:5], v[4:5], v[6:7]
	v_cvt_pk_bf16_f32 v2, v2, v3
	v_cvt_pk_bf16_f32 v3, v4, v5
	v_lshl_add_u64 v[4:5], v[10:11], 0, v[40:41]
	global_store_dwordx2 v[4:5], v[2:3], off
	s_branch .LBB0_618

; template <class EpiS>
; DI void sample_gemm(LAS unsigned char* lds, const bf16_t* A, const bf16_t* Bt, int nN, int K, const EpiS& E) {
;     const int tid = threadIdx.x, lane = tid & 63, w = __builtin_amdgcn_readfirstlane(tid >> 6), r32 = lane & 31, h = lane >> 5;
;     const int nunits = 16 * nN, kw = K >> 3, nk = kw >> 4;
;     for (int un = (int)blockIdx.x; un < nunits; un += (int)gridDim.x) {
;         const int rb = un & 3, wc = (un >> 2) & 3, pn = un >> 4;
;         const bf16_t* ap = A + (size_t)(MP + rb * 32 + r32) * K + w * kw + h * 8;
;         const bf16_t* b0p = Bt + (size_t)(pn * 256 + wc * 32 + r32) * K + w * kw + h * 8;
;         const bf16_t* b1p = b0p + (size_t)128 * K;
;         f32x16 c0, c1;
; #pragma unroll
;         for (int r = 0; r < 16; ++r) { c0[r] = 0.f; c1[r] = 0.f; }
.LBB0_932:
	s_cmpk_gt_i32 s2, 0x9f
	v_readfirstlane_b32 s4, v210
	s_cbranch_scc1 .LBB0_947
	v_and_b32_e32 v155, 63, v210
	v_lshrrev_b32_e32 v156, 6, v210
	v_and_b32_e32 v156, 7, v156
	v_lshlrev_b32_e32 v156, 13, v156
	v_add_u32_e32 v156, 0x10000, v156
	v_lshrrev_b32_e32 v182, 3, v155
	v_and_b32_e32 v165, 31, v155
	v_sub_u32_e32 v182, v182, v165
	v_lshlrev_b32_e32 v182, 11, v182
	v_and_b32_e32 v165, 7, v155
	v_lshrrev_b32_e32 v183, 5, v155
	v_sub_u32_e32 v165, v165, v183
	v_lshl_add_u32 v182, v165, 4, v182
	v_ashrrev_i32_e32 v183, 31, v182
	v_lshrrev_b32_e32 v194, 4, v155
	v_and_b32_e32 v194, 3, v194
	v_and_b32_e32 v165, 7, v155
	v_xor_b32_e32 v194, v194, v165
	v_lshlrev_b32_e32 v194, 4, v194
	v_lshrrev_b32_e32 v165, 3, v155
	v_lshl_add_u32 v194, v165, 7, v194
	v_add_u32_e32 v194, v156, v194
	v_xor_b32_e32 v195, 64, v194
	v_and_b32_e32 v165, 31, v155
	v_lshl_add_u32 v156, v165, 7, v156
	v_lshrrev_b32_e32 v165, 1, v155
	v_and_b32_e32 v165, 7, v165
	v_lshrrev_b32_e32 v155, 5, v155
	v_add_u32_e32 v244, 0, v155
	v_xor_b32_e32 v244, v244, v165
	v_lshl_add_u32 v244, v244, 4, v156
	v_add_u32_e32 v245, 2, v155
	v_xor_b32_e32 v245, v245, v165
	v_lshl_add_u32 v245, v245, 4, v156
	v_add_u32_e32 v246, 4, v155
	v_xor_b32_e32 v246, v246, v165
	v_lshl_add_u32 v246, v246, 4, v156
	v_add_u32_e32 v193, 6, v155
	v_xor_b32_e32 v193, v193, v165
	v_lshl_add_u32 v193, v193, 4, v156
	s_mov_b32 s80, 0x4000
	s_mov_b32 s81, 0
	s_mov_b32 s82, 0xffff4000
	s_mov_b32 s83, -1
	v_and_b32_e32 v6, 1, v215
	v_and_b32_e32 v37, 31, v210
	v_lshlrev_b32_e32 v34, 4, v6
	v_mov_b32_e32 v35, 0
	s_lshr_b32 s6, s4, 6
	s_mov_b32 s5, 0
	v_lshl_add_u64 v[2:3], s[34:35], 0, v[34:35]
	v_lshl_add_u64 v[4:5], s[18:19], 0, v[34:35]
	v_lshlrev_b32_e32 v6, 10, v6
	v_lshlrev_b32_e32 v7, 2, v37
	s_lshl_b32 s4, s6, 8
	v_add3_u32 v6, 0, v6, v7
	v_and_b32_e32 v7, 0x3f00, v212
	v_lshl_add_u64 v[38:39], v[2:3], 0, s[4:5]
	v_lshl_add_u64 v[40:41], v[4:5], 0, s[4:5]
	s_lshl_b32 s4, s6, 13
	v_add_u32_e32 v7, 0, v7
	v_and_b32_e32 v8, 0xf0, v212
	v_and_b32_e32 v9, 1, v213
	v_and_b32_e32 v42, 28, v214
	v_add_u32_e32 v44, s4, v6
	v_mbcnt_lo_u32_b32 v2, -1, 0
	v_lshlrev_b32_e32 v43, 7, v9
	v_cmp_eq_u32_e64 s[0:1], 0, v211
	v_lshl_or_b32 v36, v9, 5, v42
	s_lshl_b32 s10, s2, 5
	s_lshl_b32 s11, s3, 5
	s_mov_b32 s12, 0x40000
	v_add_u32_e32 v45, v7, v8
	v_mov_b32_e32 v46, 0x358637bd
	s_mov_b32 s13, 0x800000
	v_add_u32_e32 v47, 0x800, v44
	v_add_u32_e32 v48, 0x1000, v44
	v_add_u32_e32 v49, 0x1800, v44
	v_mbcnt_hi_u32_b32 v50, -1, v2
	v_mov_b32_e32 v51, 0x3e38aa3b
	s_mov_b32 s14, s2
	s_branch .LBB0_935

; template <class EpiS>
; DI void sample_gemm(LAS unsigned char* lds, const bf16_t* A, const bf16_t* Bt, int nN, int K, const EpiS& E) {
;     ...
;     for (int un = (int)blockIdx.x; un < nunits; un += (int)gridDim.x) {
;         const int rb = un & 3, wc = (un >> 2) & 3, pn = un >> 4;
;         const bf16_t* ap = A + (size_t)(MP + rb * 32 + r32) * K + w * kw + h * 8;
;         const bf16_t* b0p = Bt + (size_t)(pn * 256 + wc * 32 + r32) * K + w * kw + h * 8;
;         const bf16_t* b1p = b0p + (size_t)128 * K;
;         f32x16 c0, c1;
; #pragma unroll
;         for (int r = 0; r < 16; ++r) { c0[r] = 0.f; c1[r] = 0.f; }
; #pragma unroll 8
;         for (int ks = 0; ks < nk; ++ks) {
;             const bf16x8 a = *(const bf16x8*)(ap + ks * 16), b0 = *(const bf16x8*)(b0p + ks * 16), b1 = *(const bf16x8*)(b1p + ks * 16);
;             c0 = __builtin_amdgcn_mfma_f32_32x32x16_bf16(a, b0, c0, 0, 0, 0);
;             c1 = __builtin_amdgcn_mfma_f32_32x32x16_bf16(a, b1, c1, 0, 0, 0);
;         }
;         __syncthreads();
.LBB0_935:
	s_and_b32 s6, s10, 0x60
	s_bitset1_b32 s6, 15
	s_bfe_u32 s4, s14, 0x20002
	s_ashr_i32 s15, s14, 4
	v_or_b32_e32 v3, s6, v37
	s_lshl_b32 s7, s15, 8
	s_lshl_b32 s33, s4, 5
	v_lshlrev_b32_e32 v34, 11, v3
	s_or_b32 s7, s33, s7
	v_lshl_add_u64 v[76:77], v[38:39], 0, v[34:35]
	v_or_b32_e32 v2, s7, v37
	v_ashrrev_i32_e32 v3, 31, v2
	v_lshlrev_b64 v[2:3], 11, v[2:3]
	v_lshl_add_u64 v[78:79], v[40:41], 0, v[2:3]
	v_add_co_u32_e32 v80, vcc, s12, v78
	s_ashr_i32 s18, s14, 5
	s_nop 0
	v_addc_co_u32_e32 v81, vcc, 0, v79, vcc
	s_and_b32 s19, s15, 1
	s_mul_hi_i32 s7, s18, 0x2040000
	s_mov_b64 s[8:9], -1
	s_waitcnt vmcnt(6) lgkmcnt(0)
	s_waitcnt lgkmcnt(0)
	v_add_u32_e32 v52, s6, v157
	v_lshlrev_b32_e32 v34, 2, v52
	s_mul_i32 s6, s18, 0x2040000
	s_add_u32 s6, s24, s6
	s_addc_u32 s7, s25, s7
	s_cmp_gt_i32 s18, 1
	v_lshl_add_u64 v[158:159], v[76:77], 0, v[182:183]
	v_lshl_add_u64 v[160:161], v[78:79], 0, v[182:183]
	v_lshl_add_u64 v[180:181], v[80:81], 0, v[182:183]
	global_load_dwordx4 v[82:85], v[158:159], off
	v_lshl_add_u64 v[158:159], v[158:159], 0, s[80:81]
	global_load_dwordx4 v[86:89], v[158:159], off
	v_lshl_add_u64 v[158:159], v[158:159], 0, s[80:81]
	global_load_dwordx4 v[90:93], v[158:159], off
	v_lshl_add_u64 v[158:159], v[158:159], 0, s[80:81]
	global_load_dwordx4 v[94:97], v[158:159], off
	v_lshl_add_u64 v[158:159], v[158:159], 0, s[82:83]
	global_load_dwordx4 v[98:101], v[160:161], off
	v_lshl_add_u64 v[160:161], v[160:161], 0, s[80:81]
	global_load_dwordx4 v[102:105], v[160:161], off
	v_lshl_add_u64 v[160:161], v[160:161], 0, s[80:81]
	global_load_dwordx4 v[106:109], v[160:161], off
	v_lshl_add_u64 v[160:161], v[160:161], 0, s[80:81]
	global_load_dwordx4 v[110:113], v[160:161], off
	v_lshl_add_u64 v[160:161], v[160:161], 0, s[82:83]
	global_load_dwordx4 v[132:135], v[180:181], off
	v_lshl_add_u64 v[180:181], v[180:181], 0, s[80:81]
	global_load_dwordx4 v[136:139], v[180:181], off
	v_lshl_add_u64 v[180:181], v[180:181], 0, s[80:81]
	global_load_dwordx4 v[140:143], v[180:181], off
	v_lshl_add_u64 v[180:181], v[180:181], 0, s[80:81]
	global_load_dwordx4 v[144:147], v[180:181], off
	v_lshl_add_u64 v[180:181], v[180:181], 0, s[82:83]
	global_load_dwordx4 v[148:151], v[158:159], off offset:128
	v_lshl_add_u64 v[158:159], v[158:159], 0, s[80:81]
	global_load_dwordx4 v[166:169], v[158:159], off offset:128
	v_lshl_add_u64 v[158:159], v[158:159], 0, s[80:81]
	global_load_dwordx4 v[170:173], v[158:159], off offset:128
	v_lshl_add_u64 v[158:159], v[158:159], 0, s[80:81]
	global_load_dwordx4 v[174:177], v[158:159], off offset:128
	global_load_dwordx4 v[198:201], v[160:161], off offset:128
	v_lshl_add_u64 v[160:161], v[160:161], 0, s[80:81]
	global_load_dwordx4 v[202:205], v[160:161], off offset:128
	v_lshl_add_u64 v[160:161], v[160:161], 0, s[80:81]
	global_load_dwordx4 v[216:219], v[160:161], off offset:128
	v_lshl_add_u64 v[160:161], v[160:161], 0, s[80:81]
	global_load_dwordx4 v[220:223], v[160:161], off offset:128
	global_load_dwordx4 v[224:227], v[180:181], off offset:128
	v_lshl_add_u64 v[180:181], v[180:181], 0, s[80:81]
	global_load_dwordx4 v[228:231], v[180:181], off offset:128
	v_lshl_add_u64 v[180:181], v[180:181], 0, s[80:81]
	global_load_dwordx4 v[232:235], v[180:181], off offset:128
	v_lshl_add_u64 v[180:181], v[180:181], 0, s[80:81]
	global_load_dwordx4 v[236:239], v[180:181], off offset:128
	s_waitcnt vmcnt(16)
	ds_write_b128 v194, v[82:85]
	ds_write_b128 v195, v[86:89] offset:1024
	ds_write_b128 v194, v[90:93] offset:2048
	ds_write_b128 v195, v[94:97] offset:3072
	ds_write_b128 v194, v[98:101] offset:4096
	ds_write_b128 v195, v[102:105] offset:5120
	ds_write_b128 v194, v[106:109] offset:6144
	ds_write_b128 v195, v[110:113] offset:7168
	ds_read_b128 v[82:85], v244
	ds_read_b128 v[86:89], v245
	ds_read_b128 v[90:93], v246
	ds_read_b128 v[94:97], v193
	ds_read_b128 v[98:101], v244 offset:4096
	ds_read_b128 v[102:105], v245 offset:4096
	ds_read_b128 v[106:109], v246 offset:4096
	ds_read_b128 v[110:113], v193 offset:4096
	s_waitcnt lgkmcnt(0)
	v_mfma_f32_32x32x16_bf16 v[2:17], v[82:85], v[98:101], 0
	v_mfma_f32_32x32x16_bf16 v[2:17], v[86:89], v[102:105], v[2:17]
	v_mfma_f32_32x32x16_bf16 v[2:17], v[90:93], v[106:109], v[2:17]
	v_mfma_f32_32x32x16_bf16 v[2:17], v[94:97], v[110:113], v[2:17]
	s_waitcnt vmcnt(12)
	ds_write_b128 v194, v[132:135] offset:4096
	ds_write_b128 v195, v[136:139] offset:5120
	ds_write_b128 v194, v[140:143] offset:6144
	ds_write_b128 v195, v[144:147] offset:7168
	ds_read_b128 v[132:135], v244 offset:4096
	ds_read_b128 v[136:139], v245 offset:4096
	ds_read_b128 v[140:143], v246 offset:4096
	ds_read_b128 v[144:147], v193 offset:4096
	s_waitcnt lgkmcnt(0)
	v_mfma_f32_32x32x16_bf16 v[18:33], v[82:85], v[132:135], 0
	v_mfma_f32_32x32x16_bf16 v[18:33], v[86:89], v[136:139], v[18:33]
	v_mfma_f32_32x32x16_bf16 v[18:33], v[90:93], v[140:143], v[18:33]
	v_mfma_f32_32x32x16_bf16 v[18:33], v[94:97], v[144:147], v[18:33]
	s_waitcnt vmcnt(4)
	ds_write_b128 v194, v[148:151]
	ds_write_b128 v195, v[166:169] offset:1024
	ds_write_b128 v194, v[170:173] offset:2048
	ds_write_b128 v195, v[174:177] offset:3072
	ds_write_b128 v194, v[198:201] offset:4096
	ds_write_b128 v195, v[202:205] offset:5120
	ds_write_b128 v194, v[216:219] offset:6144
	ds_write_b128 v195, v[220:223] offset:7168
	ds_read_b128 v[148:151], v244
	ds_read_b128 v[166:169], v245
	ds_read_b128 v[170:173], v246
	ds_read_b128 v[174:177], v193
	ds_read_b128 v[198:201], v244 offset:4096
	ds_read_b128 v[202:205], v245 offset:4096
	ds_read_b128 v[216:219], v246 offset:4096
	ds_read_b128 v[220:223], v193 offset:4096
	s_waitcnt lgkmcnt(0)
	v_mfma_f32_32x32x16_bf16 v[2:17], v[148:151], v[198:201], v[2:17]
	v_mfma_f32_32x32x16_bf16 v[2:17], v[166:169], v[202:205], v[2:17]
	v_mfma_f32_32x32x16_bf16 v[2:17], v[170:173], v[216:219], v[2:17]
	v_mfma_f32_32x32x16_bf16 v[2:17], v[174:177], v[220:223], v[2:17]
	s_waitcnt vmcnt(0)
	ds_write_b128 v194, v[224:227] offset:4096
	ds_write_b128 v195, v[228:231] offset:5120
	ds_write_b128 v194, v[232:235] offset:6144
	ds_write_b128 v195, v[236:239] offset:7168
	ds_read_b128 v[224:227], v244 offset:4096
	ds_read_b128 v[228:231], v245 offset:4096
	ds_read_b128 v[232:235], v246 offset:4096
	ds_read_b128 v[236:239], v193 offset:4096
	s_waitcnt lgkmcnt(0)
	v_mfma_f32_32x32x16_bf16 v[18:33], v[148:151], v[224:227], v[18:33]
	v_mfma_f32_32x32x16_bf16 v[18:33], v[166:169], v[228:231], v[18:33]
	v_mfma_f32_32x32x16_bf16 v[18:33], v[170:173], v[232:235], v[18:33]
	v_mfma_f32_32x32x16_bf16 v[18:33], v[174:177], v[236:239], v[18:33]
	s_barrier
; #define LAS __attribute__((address_space(3)))
; DI float row_rstd(const float* SS, int row) { return rsqrtf(SS[row] * (1.0f / 1024.0f) + 1e-6f); }
; DI float red16(float v) { v += __shfl_xor(v, 1); v += __shfl_xor(v, 2); v += __shfl_xor(v, 4); v += __shfl_xor(v, 8); return v; }
;     DI void operator()(const f32x4 v, int row, int pn, int wc, int bj, int cl) const {
;         const int typ = pn >> 1, ph = pn & 1;
;         bf16_t* O = QKVUS + (size_t)typ * ((size_t)MT * MW);
;         const float rs = row_rstd(SS, row);
;         const f32x4 x = v * rs;
;         if (typ < 2) {
;             const int head = ph * 4 + wc, dd = 32 * bj + cl;
;             const float ssq = red16((x[0] * x[0] + x[1] * x[1]) + (x[2] * x[2] + x[3] * x[3]));
;             const float r = rsqrtf(ssq * (1.0f / 64.0f) + 1e-6f);
;             const f32x4 gv = *(const f32x4*)((typ == 0 ? qg : kg) + dd);
;             const f32x4 o = x * r * gv;
;             *(u32x2*)(O + (size_t)row * MW + head * 64 + dd) = pk4(o * (typ == 0 ? QSCALE : 1.0f));
;             if (typ == 1) *(f32x4*)(out + O_KS + (size_t)(row - MP) * 512 + head * 64 + dd) = o;
;         } else {
;             const int col = ph * 256 + bj * 128 + wc * 32 + cl;
;             *(u32x2*)(O + (size_t)row * MW + col) = pk4(x);
;             if (typ == 2) *(f32x4*)(out + O_VS + (size_t)(row - MP) * 512 + col) = x;
;             if (typ == 4) {
;                 const float s1 = red16((x[0] + x[1]) + (x[2] + x[3])), s2 = red16((x[0] * x[0] + x[1] * x[1]) + (x[2] * x[2] + x[3] * x[3]));
;                 if ((threadIdx.x & 15) == 0) *(f32x2*)(SVST + ((size_t)row * 8 + ph * 4 + wc) * 2) = (f32x2){s1, s2};
;             }
; template <class EpiS>
; DI void sample_gemm(LAS unsigned char* lds, const bf16_t* A, const bf16_t* Bt, int nN, int K, const EpiS& E) {
;     ...
;         __syncthreads();
;         LAS float* part = (LAS float*)(lds + w * 8192);
; #pragma unroll
;         for (int r = 0; r < 16; ++r) { const int row = (r & 3) + 8 * (r >> 2) + 4 * h; part[row * 64 + r32] = c0[r]; part[row * 64 + 32 + r32] = c1[r]; }
;         __syncthreads();
;         f32x4 v = (f32x4){0.f, 0.f, 0.f, 0.f};
; #pragma unroll
;         for (int ww = 0; ww < 8; ++ww) v += *(const LAS f32x4*)(lds + ww * 8192 + (tid >> 4) * 256 + (tid & 15) * 16);
;         E(v, MP + rb * 32 + (tid >> 4), pn, wc, (tid >> 3) & 1, 4 * (tid & 7));
	s_nop 11
	ds_write2_b32 v44, v2, v18 offset1:32
	ds_write2_b32 v44, v3, v19 offset0:64 offset1:96
	ds_write2_b32 v44, v4, v20 offset0:128 offset1:160
	ds_write2_b32 v44, v5, v21 offset0:192 offset1:224
	ds_write2_b32 v47, v6, v22 offset1:32
	ds_write2_b32 v47, v7, v23 offset0:64 offset1:96
	ds_write2_b32 v47, v8, v24 offset0:128 offset1:160
	ds_write2_b32 v47, v9, v25 offset0:192 offset1:224
	ds_write2_b32 v48, v10, v26 offset1:32
	ds_write2_b32 v48, v11, v27 offset0:64 offset1:96
	ds_write2_b32 v48, v12, v28 offset0:128 offset1:160
	ds_write2_b32 v48, v13, v29 offset0:192 offset1:224
	ds_write2_b32 v49, v14, v30 offset1:32
	ds_write2_b32 v49, v15, v31 offset0:64 offset1:96
	ds_write2_b32 v49, v16, v32 offset0:128 offset1:160
	ds_write2_b32 v49, v17, v33 offset0:192 offset1:224
	s_waitcnt lgkmcnt(0)
	s_barrier
	global_load_dword v34, v34, s[16:17]
	ds_read_b128 v[2:5], v45
	ds_read_b128 v[6:9], v45 offset:8192
	ds_read_b128 v[10:13], v45 offset:16384
	ds_read_b128 v[14:17], v45 offset:24576
	ds_read_b128 v[18:21], v45 offset:32768
	ds_read_b128 v[22:25], v45 offset:40960
	ds_read_b128 v[26:29], v45 offset:49152
	ds_read_b128 v[30:33], v45 offset:57344
	s_waitcnt lgkmcnt(7)
	v_pk_add_f32 v[2:3], v[2:3], 0 op_sel_hi:[1,0]
	v_pk_add_f32 v[4:5], v[4:5], 0 op_sel_hi:[1,0]
	s_waitcnt lgkmcnt(6)
	v_pk_add_f32 v[2:3], v[2:3], v[6:7]
	v_pk_add_f32 v[4:5], v[4:5], v[8:9]
	s_waitcnt lgkmcnt(5)
	v_pk_add_f32 v[2:3], v[2:3], v[10:11]
	v_pk_add_f32 v[4:5], v[4:5], v[12:13]
	s_waitcnt lgkmcnt(4)
	v_pk_add_f32 v[2:3], v[2:3], v[14:15]
	v_pk_add_f32 v[4:5], v[4:5], v[16:17]
	s_waitcnt lgkmcnt(3)
	v_pk_add_f32 v[2:3], v[2:3], v[18:19]
	v_pk_add_f32 v[4:5], v[4:5], v[20:21]
	s_waitcnt lgkmcnt(2)
	v_pk_add_f32 v[2:3], v[2:3], v[22:23]
	v_pk_add_f32 v[4:5], v[4:5], v[24:25]
	s_waitcnt lgkmcnt(1)
	v_pk_add_f32 v[2:3], v[2:3], v[26:27]
	v_pk_add_f32 v[4:5], v[4:5], v[28:29]
	s_waitcnt lgkmcnt(0)
	v_pk_add_f32 v[2:3], v[2:3], v[30:31]
	v_pk_add_f32 v[4:5], v[4:5], v[32:33]
	s_waitcnt vmcnt(0)
	v_fmamk_f32 v6, v34, 0x3a800000, v46
	v_mul_f32_e32 v7, 0x4b800000, v6
	v_cmp_gt_f32_e32 vcc, s13, v6
	v_lshlrev_b32_e32 v34, 10, v52
	s_nop 0
	v_cndmask_b32_e32 v6, v6, v7, vcc
	v_rsq_f32_e32 v6, v6
	s_nop 0
	v_mul_f32_e32 v7, 0x45800000, v6
	v_cndmask_b32_e32 v6, v6, v7, vcc
	v_pk_mul_f32 v[2:3], v[2:3], v[6:7] op_sel_hi:[1,0]
	v_pk_mul_f32 v[4:5], v[4:5], v[6:7] op_sel_hi:[1,0]
	s_cbranch_scc0 .LBB0_944
	v_lshl_or_b32 v6, s19, 8, v43
	v_or3_b32 v6, v6, s33, v42
	v_lshl_add_u64 v[10:11], s[6:7], 0, v[34:35]
	v_lshlrev_b32_e32 v12, 1, v6
	v_mov_b32_e32 v13, v35
	v_cvt_pk_bf16_f32 v8, v2, v3
	v_cvt_pk_bf16_f32 v9, v4, v5
	v_lshl_add_u64 v[10:11], v[10:11], 0, v[12:13]
	s_cmp_gt_i32 s18, 3
	global_store_dwordx2 v[10:11], v[8:9], off
	s_cbranch_scc0 .LBB0_940
	v_and_b32_e32 v8, 64, v50
	v_xor_b32_e32 v7, 1, v50
	v_add_u32_e32 v16, 64, v8
	v_cmp_lt_i32_e32 vcc, v7, v16
	v_mul_f32_e32 v9, v2, v2
	v_mul_f32_e32 v11, v3, v3
	v_mul_f32_e32 v13, v4, v4
	v_mul_f32_e32 v15, v5, v5
	v_mov_b32_e32 v8, v2
	v_mov_b32_e32 v10, v3
	v_mov_b32_e32 v12, v4
	v_mov_b32_e32 v14, v5
	v_cndmask_b32_e32 v7, v50, v7, vcc
	v_pk_add_f32 v[8:9], v[8:9], v[10:11]
	v_pk_add_f32 v[10:11], v[12:13], v[14:15]
	v_lshlrev_b32_e32 v7, 2, v7
	v_pk_add_f32 v[8:9], v[8:9], v[10:11]
	ds_bpermute_b32 v10, v7, v8
	ds_bpermute_b32 v11, v7, v9
	v_xor_b32_e32 v7, 2, v50
	v_cmp_lt_i32_e32 vcc, v7, v16
	s_waitcnt lgkmcnt(0)
	v_pk_add_f32 v[8:9], v[8:9], v[10:11]
	v_cndmask_b32_e32 v7, v50, v7, vcc
	v_lshlrev_b32_e32 v7, 2, v7
	ds_bpermute_b32 v10, v7, v8
	ds_bpermute_b32 v11, v7, v9
	v_xor_b32_e32 v7, 4, v50
	v_cmp_lt_i32_e32 vcc, v7, v16
	s_waitcnt lgkmcnt(0)
	v_pk_add_f32 v[8:9], v[8:9], v[10:11]
	v_cndmask_b32_e32 v7, v50, v7, vcc
	v_lshlrev_b32_e32 v7, 2, v7
	ds_bpermute_b32 v10, v7, v8
	ds_bpermute_b32 v11, v7, v9
	v_xor_b32_e32 v7, 8, v50
	v_cmp_lt_i32_e32 vcc, v7, v16
	s_waitcnt lgkmcnt(0)
	v_pk_add_f32 v[8:9], v[8:9], v[10:11]
	v_cndmask_b32_e32 v7, v50, v7, vcc
	v_lshlrev_b32_e32 v7, 2, v7
	ds_bpermute_b32 v10, v7, v8
	ds_bpermute_b32 v11, v7, v9
	s_and_saveexec_b64 s[8:9], s[0:1]
	s_cbranch_execz .LBB0_939
	s_lshl_b32 s33, s19, 2
	v_lshl_or_b32 v7, v52, 3, s33
	v_or_b32_e32 v7, s4, v7
	v_readlane_b32 s50, v247, 7
	v_lshlrev_b32_e32 v7, 3, v7
	s_waitcnt lgkmcnt(0)
	v_pk_add_f32 v[8:9], v[8:9], v[10:11]
	v_readlane_b32 s51, v247, 8
	s_nop 4
	global_store_dwordx2 v7, v[8:9], s[50:51]

; template <class EpiS>
; DI void sample_gemm(LAS unsigned char* lds, const bf16_t* A, const bf16_t* Bt, int nN, int K, const EpiS& E) {
;     const int tid = threadIdx.x, lane = tid & 63, w = __builtin_amdgcn_readfirstlane(tid >> 6), r32 = lane & 31, h = lane >> 5;
;     const int nunits = 16 * nN, kw = K >> 3, nk = kw >> 4;
;     for (int un = (int)blockIdx.x; un < nunits; un += (int)gridDim.x) {
;         const int rb = un & 3, wc = (un >> 2) & 3, pn = un >> 4;
;         const bf16_t* ap = A + (size_t)(MP + rb * 32 + r32) * K + w * kw + h * 8;
;         const bf16_t* b0p = Bt + (size_t)(pn * 256 + wc * 32 + r32) * K + w * kw + h * 8;
;         const bf16_t* b1p = b0p + (size_t)128 * K;
;         f32x16 c0, c1;
; #pragma unroll
;         for (int r = 0; r < 16; ++r) { c0[r] = 0.f; c1[r] = 0.f; }
.LBB0_1362:
	s_cmp_gt_i32 s2, 63
	v_readfirstlane_b32 s0, v189
	s_cbranch_scc1 .LBB0_1367
	v_and_b32_e32 v155, 63, v189
	v_lshrrev_b32_e32 v156, 6, v189
	v_and_b32_e32 v156, 7, v156
	v_lshlrev_b32_e32 v156, 13, v156
	v_add_u32_e32 v156, 0x10000, v156
	v_lshrrev_b32_e32 v182, 3, v155
	v_and_b32_e32 v165, 31, v155
	v_sub_u32_e32 v182, v182, v165
	v_lshlrev_b32_e32 v182, 11, v182
	v_and_b32_e32 v165, 7, v155
	v_lshrrev_b32_e32 v183, 5, v155
	v_sub_u32_e32 v165, v165, v183
	v_lshl_add_u32 v182, v165, 4, v182
	v_ashrrev_i32_e32 v183, 31, v182
	v_lshrrev_b32_e32 v194, 4, v155
	v_and_b32_e32 v194, 3, v194
	v_and_b32_e32 v165, 7, v155
	v_xor_b32_e32 v194, v194, v165
	v_lshlrev_b32_e32 v194, 4, v194
	v_lshrrev_b32_e32 v165, 3, v155
	v_lshl_add_u32 v194, v165, 7, v194
	v_add_u32_e32 v194, v156, v194
	v_xor_b32_e32 v195, 64, v194
	v_and_b32_e32 v165, 31, v155
	v_lshl_add_u32 v156, v165, 7, v156
	v_lshrrev_b32_e32 v165, 1, v155
	v_and_b32_e32 v165, 7, v165
	v_lshrrev_b32_e32 v155, 5, v155
	v_add_u32_e32 v244, 0, v155
	v_xor_b32_e32 v244, v244, v165
	v_lshl_add_u32 v244, v244, 4, v156
	v_add_u32_e32 v245, 2, v155
	v_xor_b32_e32 v245, v245, v165
	v_lshl_add_u32 v245, v245, 4, v156
	v_add_u32_e32 v246, 4, v155
	v_xor_b32_e32 v246, v246, v165
	v_lshl_add_u32 v246, v246, 4, v156
	v_add_u32_e32 v193, 6, v155
	v_xor_b32_e32 v193, v193, v165
	v_lshl_add_u32 v193, v193, 4, v156
	s_mov_b32 s80, 0x4000
	s_mov_b32 s81, 0
	s_mov_b32 s82, 0xffff4000
	s_mov_b32 s83, -1
	s_lshr_b32 s4, s0, 6
	s_lshl_b32 s5, s4, 8
	v_bfe_u32 v2, v189, 5, 1
	s_add_u32 s0, s26, s5
	s_addc_u32 s1, s27, 0
	v_lshlrev_b32_e32 v34, 4, v2
	v_mov_b32_e32 v35, 0
	v_lshl_add_u64 v[36:37], s[0:1], 0, v[34:35]
	s_add_u32 s0, s33, s5
	s_addc_u32 s1, s46, 0
	v_and_b32_e32 v40, 31, v189
	v_lshl_add_u64 v[38:39], s[0:1], 0, v[34:35]
	s_lshl_b32 s0, s4, 13
	s_add_i32 s0, s0, 0
	v_lshlrev_b32_e32 v2, 10, v2
	s_waitcnt lgkmcnt(0)
	v_lshlrev_b32_e32 v3, 2, v40
	v_add3_u32 v41, s0, v2, v3
	v_and_b32_e32 v4, 28, v192
	s_movk_i32 s0, 0x80
	v_and_or_b32 v42, v191, s0, v4
	v_mbcnt_lo_u32_b32 v4, -1, 0
	v_mbcnt_hi_u32_b32 v4, -1, v4
	v_and_b32_e32 v6, 64, v4
	v_xor_b32_e32 v5, 1, v4
	v_add_u32_e32 v6, 64, v6
	v_cmp_lt_i32_e32 vcc, v5, v6
	v_and_b32_e32 v2, 0x3f00, v191
	v_add_u32_e32 v2, 0, v2
	v_cndmask_b32_e32 v5, v4, v5, vcc
	v_lshlrev_b32_e32 v43, 2, v5
	v_xor_b32_e32 v5, 2, v4
	v_cmp_lt_i32_e32 vcc, v5, v6
	v_and_b32_e32 v3, 0xf0, v191
	s_lshl_b32 s4, s2, 3
	v_cndmask_b32_e32 v5, v4, v5, vcc
	v_lshlrev_b32_e32 v44, 2, v5
	v_xor_b32_e32 v5, 4, v4
	v_cmp_lt_i32_e32 vcc, v5, v6
	s_lshl_b32 s5, s3, 3
	s_lshl_b32 s10, s2, 4
	v_cndmask_b32_e32 v5, v4, v5, vcc
	v_lshlrev_b32_e32 v45, 2, v5
	v_xor_b32_e32 v5, 8, v4
	v_cmp_lt_i32_e32 vcc, v5, v6
	s_lshl_b32 s11, s3, 4
	s_lshl_b32 s12, s2, 5
	v_cndmask_b32_e32 v4, v4, v5, vcc
	v_lshlrev_b32_e32 v46, 2, v4
	v_cmp_eq_u32_e32 vcc, 0, v190
	s_lshl_b32 s13, s3, 5
	s_mov_b32 s14, 0x40000
	v_add_u32_e32 v47, v2, v3
	v_add_u32_e32 v48, 0x800, v41
	v_add_u32_e32 v49, 0x1000, v41
	v_add_u32_e32 v50, 0x1800, v41
	s_mov_b32 s15, s2
	s_branch .LBB0_1365

; template <class EpiS>
; DI void sample_gemm(LAS unsigned char* lds, const bf16_t* A, const bf16_t* Bt, int nN, int K, const EpiS& E) {
;     ...
;     for (int un = (int)blockIdx.x; un < nunits; un += (int)gridDim.x) {
;         const int rb = un & 3, wc = (un >> 2) & 3, pn = un >> 4;
;         const bf16_t* ap = A + (size_t)(MP + rb * 32 + r32) * K + w * kw + h * 8;
;         const bf16_t* b0p = Bt + (size_t)(pn * 256 + wc * 32 + r32) * K + w * kw + h * 8;
;         const bf16_t* b1p = b0p + (size_t)128 * K;
;         f32x16 c0, c1;
; #pragma unroll
;         for (int r = 0; r < 16; ++r) { c0[r] = 0.f; c1[r] = 0.f; }
; #pragma unroll 8
;         for (int ks = 0; ks < nk; ++ks) {
;             const bf16x8 a = *(const bf16x8*)(ap + ks * 16), b0 = *(const bf16x8*)(b0p + ks * 16), b1 = *(const bf16x8*)(b1p + ks * 16);
;             c0 = __builtin_amdgcn_mfma_f32_32x32x16_bf16(a, b0, c0, 0, 0, 0);
;             c1 = __builtin_amdgcn_mfma_f32_32x32x16_bf16(a, b1, c1, 0, 0, 0);
;         }
;         __syncthreads();
.LBB0_1365:
	s_and_b32 s0, s12, 0x60
	s_or_b32 s16, s0, 0x8000
	s_waitcnt lgkmcnt(0)
	v_or_b32_e32 v3, s16, v40
	s_and_b32 s0, s10, 0xffffff00
	s_and_b32 s1, s4, 0x60
	v_lshlrev_b32_e32 v34, 11, v3
	s_or_b32 s17, s0, s1
	v_lshl_add_u64 v[76:77], v[36:37], 0, v[34:35]
	v_or_b32_e32 v2, s17, v40
	v_ashrrev_i32_e32 v3, 31, v2
	v_lshlrev_b64 v[2:3], 11, v[2:3]
	v_lshl_add_u64 v[78:79], v[38:39], 0, v[2:3]
	v_add_co_u32_e64 v80, s[0:1], s14, v78
	v_add_u32_e32 v51, s16, v188
	s_nop 0
	v_addc_co_u32_e64 v81, s[0:1], 0, v79, s[0:1]
	v_lshlrev_b32_e32 v34, 11, v51
	v_or_b32_e32 v60, s17, v42
	v_ashrrev_i32_e32 v61, 31, v60
	v_lshl_add_u64 v[56:57], s[34:35], 0, v[34:35]
	v_lshl_add_u64 v[56:57], v[60:61], 1, v[56:57]
	v_lshl_add_u64 v[158:159], v[76:77], 0, v[182:183]
	v_lshl_add_u64 v[160:161], v[78:79], 0, v[182:183]
	v_lshl_add_u64 v[180:181], v[80:81], 0, v[182:183]
	global_load_dwordx4 v[82:85], v[158:159], off
	v_lshl_add_u64 v[158:159], v[158:159], 0, s[80:81]
	global_load_dwordx4 v[86:89], v[158:159], off
	v_lshl_add_u64 v[158:159], v[158:159], 0, s[80:81]
	global_load_dwordx4 v[90:93], v[158:159], off
	v_lshl_add_u64 v[158:159], v[158:159], 0, s[80:81]
	global_load_dwordx4 v[94:97], v[158:159], off
	v_lshl_add_u64 v[158:159], v[158:159], 0, s[82:83]
	global_load_dwordx4 v[98:101], v[160:161], off
	v_lshl_add_u64 v[160:161], v[160:161], 0, s[80:81]
	global_load_dwordx4 v[102:105], v[160:161], off
	v_lshl_add_u64 v[160:161], v[160:161], 0, s[80:81]
	global_load_dwordx4 v[106:109], v[160:161], off
	v_lshl_add_u64 v[160:161], v[160:161], 0, s[80:81]
	global_load_dwordx4 v[110:113], v[160:161], off
	v_lshl_add_u64 v[160:161], v[160:161], 0, s[82:83]
	global_load_dwordx4 v[132:135], v[180:181], off
	v_lshl_add_u64 v[180:181], v[180:181], 0, s[80:81]
	global_load_dwordx4 v[136:139], v[180:181], off
	v_lshl_add_u64 v[180:181], v[180:181], 0, s[80:81]
	global_load_dwordx4 v[140:143], v[180:181], off
	v_lshl_add_u64 v[180:181], v[180:181], 0, s[80:81]
	global_load_dwordx4 v[144:147], v[180:181], off
	v_lshl_add_u64 v[180:181], v[180:181], 0, s[82:83]
	global_load_dwordx4 v[148:151], v[158:159], off offset:128
	v_lshl_add_u64 v[158:159], v[158:159], 0, s[80:81]
	global_load_dwordx4 v[166:169], v[158:159], off offset:128
	v_lshl_add_u64 v[158:159], v[158:159], 0, s[80:81]
	global_load_dwordx4 v[170:173], v[158:159], off offset:128
	v_lshl_add_u64 v[158:159], v[158:159], 0, s[80:81]
	global_load_dwordx4 v[174:177], v[158:159], off offset:128
	global_load_dwordx4 v[198:201], v[160:161], off offset:128
	v_lshl_add_u64 v[160:161], v[160:161], 0, s[80:81]
	global_load_dwordx4 v[202:205], v[160:161], off offset:128
	v_lshl_add_u64 v[160:161], v[160:161], 0, s[80:81]
	global_load_dwordx4 v[216:219], v[160:161], off offset:128
	v_lshl_add_u64 v[160:161], v[160:161], 0, s[80:81]
	global_load_dwordx4 v[220:223], v[160:161], off offset:128
	global_load_dwordx4 v[224:227], v[180:181], off offset:128
	v_lshl_add_u64 v[180:181], v[180:181], 0, s[80:81]
	global_load_dwordx4 v[228:231], v[180:181], off offset:128
	v_lshl_add_u64 v[180:181], v[180:181], 0, s[80:81]
	global_load_dwordx4 v[232:235], v[180:181], off offset:128
	v_lshl_add_u64 v[180:181], v[180:181], 0, s[80:81]
	global_load_dwordx4 v[236:239], v[180:181], off offset:128
	s_waitcnt vmcnt(16)
	ds_write_b128 v194, v[82:85]
	ds_write_b128 v195, v[86:89] offset:1024
	ds_write_b128 v194, v[90:93] offset:2048
	ds_write_b128 v195, v[94:97] offset:3072
	ds_write_b128 v194, v[98:101] offset:4096
	ds_write_b128 v195, v[102:105] offset:5120
	ds_write_b128 v194, v[106:109] offset:6144
	ds_write_b128 v195, v[110:113] offset:7168
	ds_read_b128 v[82:85], v244
	ds_read_b128 v[86:89], v245
	ds_read_b128 v[90:93], v246
	ds_read_b128 v[94:97], v193
	ds_read_b128 v[98:101], v244 offset:4096
	ds_read_b128 v[102:105], v245 offset:4096
	ds_read_b128 v[106:109], v246 offset:4096
	ds_read_b128 v[110:113], v193 offset:4096
	s_waitcnt lgkmcnt(0)
	v_mfma_f32_32x32x16_bf16 v[2:17], v[82:85], v[98:101], 0
	v_mfma_f32_32x32x16_bf16 v[2:17], v[86:89], v[102:105], v[2:17]
	v_mfma_f32_32x32x16_bf16 v[2:17], v[90:93], v[106:109], v[2:17]
	v_mfma_f32_32x32x16_bf16 v[2:17], v[94:97], v[110:113], v[2:17]
	s_waitcnt vmcnt(12)
	ds_write_b128 v194, v[132:135] offset:4096
	ds_write_b128 v195, v[136:139] offset:5120
	ds_write_b128 v194, v[140:143] offset:6144
	ds_write_b128 v195, v[144:147] offset:7168
	ds_read_b128 v[132:135], v244 offset:4096
	ds_read_b128 v[136:139], v245 offset:4096
	ds_read_b128 v[140:143], v246 offset:4096
	ds_read_b128 v[144:147], v193 offset:4096
	s_waitcnt lgkmcnt(0)
	v_mfma_f32_32x32x16_bf16 v[18:33], v[82:85], v[132:135], 0
	v_mfma_f32_32x32x16_bf16 v[18:33], v[86:89], v[136:139], v[18:33]
	v_mfma_f32_32x32x16_bf16 v[18:33], v[90:93], v[140:143], v[18:33]
	v_mfma_f32_32x32x16_bf16 v[18:33], v[94:97], v[144:147], v[18:33]
	s_waitcnt vmcnt(4)
	ds_write_b128 v194, v[148:151]
	ds_write_b128 v195, v[166:169] offset:1024
	ds_write_b128 v194, v[170:173] offset:2048
	ds_write_b128 v195, v[174:177] offset:3072
	ds_write_b128 v194, v[198:201] offset:4096
	ds_write_b128 v195, v[202:205] offset:5120
	ds_write_b128 v194, v[216:219] offset:6144
	ds_write_b128 v195, v[220:223] offset:7168
	ds_read_b128 v[148:151], v244
	ds_read_b128 v[166:169], v245
	ds_read_b128 v[170:173], v246
	ds_read_b128 v[174:177], v193
	ds_read_b128 v[198:201], v244 offset:4096
	ds_read_b128 v[202:205], v245 offset:4096
	ds_read_b128 v[216:219], v246 offset:4096
	ds_read_b128 v[220:223], v193 offset:4096
	s_waitcnt lgkmcnt(0)
	v_mfma_f32_32x32x16_bf16 v[2:17], v[148:151], v[198:201], v[2:17]
	v_mfma_f32_32x32x16_bf16 v[2:17], v[166:169], v[202:205], v[2:17]
	v_mfma_f32_32x32x16_bf16 v[2:17], v[170:173], v[216:219], v[2:17]
	v_mfma_f32_32x32x16_bf16 v[2:17], v[174:177], v[220:223], v[2:17]
	s_waitcnt vmcnt(0)
	ds_write_b128 v194, v[224:227] offset:4096
	ds_write_b128 v195, v[228:231] offset:5120
	ds_write_b128 v194, v[232:235] offset:6144
	ds_write_b128 v195, v[236:239] offset:7168
	ds_read_b128 v[224:227], v244 offset:4096
	ds_read_b128 v[228:231], v245 offset:4096
	ds_read_b128 v[232:235], v246 offset:4096
	ds_read_b128 v[236:239], v193 offset:4096
	s_waitcnt lgkmcnt(0)
	v_mfma_f32_32x32x16_bf16 v[18:33], v[148:151], v[224:227], v[18:33]
	v_mfma_f32_32x32x16_bf16 v[18:33], v[166:169], v[228:231], v[18:33]
	v_mfma_f32_32x32x16_bf16 v[18:33], v[170:173], v[232:235], v[18:33]
	v_mfma_f32_32x32x16_bf16 v[18:33], v[174:177], v[236:239], v[18:33]
	s_barrier
; #define LAS __attribute__((address_space(3)))
; DI float bflo(unsigned u) { return __uint_as_float(u << 16); }
; DI float bfhi(unsigned u) { return __uint_as_float(u & 0xffff0000u); }
; DI float red16(float v) { v += __shfl_xor(v, 1); v += __shfl_xor(v, 2); v += __shfl_xor(v, 4); v += __shfl_xor(v, 8); return v; }
; DI u32x2 pk4(const f32x4 a) { return (u32x2){pk2(a[0], a[1]), pk2(a[2], a[3])}; }
;     DI void operator()(const f32x4 v, int row, int pn, int wc, int bj, int cl) const {
;         const int col = pn * 256 + bj * 128 + wc * 32 + cl;
;         f32x4 x;
;         if (MODE == 0) x = *(const f32x4*)(xin + (size_t)row * D + col);
;         else { const u32x2 w = *(const u32x2*)(XN + (size_t)row * D + col); x = (f32x4){bflo(w.x), bfhi(w.x), bflo(w.y), bfhi(w.y)}; }
;         x += v;
;         if (MODE == 2) *(f32x4*)(out + (size_t)row * D + col) = x;
;         else {
;             *(u32x2*)(XN + (size_t)row * D + col) = pk4(x);
;             const float ssq = red16((x[0] * x[0] + x[1] * x[1]) + (x[2] * x[2] + x[3] * x[3]));
;             if ((threadIdx.x & 15) == 0) atomicAdd(SS + row, ssq);
;         }
; template <class EpiS>
; DI void sample_gemm(LAS unsigned char* lds, const bf16_t* A, const bf16_t* Bt, int nN, int K, const EpiS& E) {
;     ...
;         __syncthreads();
;         LAS float* part = (LAS float*)(lds + w * 8192);
; #pragma unroll
;         for (int r = 0; r < 16; ++r) { const int row = (r & 3) + 8 * (r >> 2) + 4 * h; part[row * 64 + r32] = c0[r]; part[row * 64 + 32 + r32] = c1[r]; }
;         __syncthreads();
;         f32x4 v = (f32x4){0.f, 0.f, 0.f, 0.f};
; #pragma unroll
;         for (int ww = 0; ww < 8; ++ww) v += *(const LAS f32x4*)(lds + ww * 8192 + (tid >> 4) * 256 + (tid & 15) * 16);
;         E(v, MP + rb * 32 + (tid >> 4), pn, wc, (tid >> 3) & 1, 4 * (tid & 7));
	s_nop 11
	ds_write2_b32 v41, v2, v18 offset1:32
	ds_write2_b32 v41, v3, v19 offset0:64 offset1:96
	ds_write2_b32 v41, v4, v20 offset0:128 offset1:160
	ds_write2_b32 v41, v5, v21 offset0:192 offset1:224
	ds_write2_b32 v48, v6, v22 offset1:32
	ds_write2_b32 v48, v7, v23 offset0:64 offset1:96
	ds_write2_b32 v48, v8, v24 offset0:128 offset1:160
	ds_write2_b32 v48, v9, v25 offset0:192 offset1:224
	ds_write2_b32 v49, v10, v26 offset1:32
	ds_write2_b32 v49, v11, v27 offset0:64 offset1:96
	ds_write2_b32 v49, v12, v28 offset0:128 offset1:160
	ds_write2_b32 v49, v13, v29 offset0:192 offset1:224
	ds_write2_b32 v50, v14, v30 offset1:32
	ds_write2_b32 v50, v15, v31 offset0:64 offset1:96
	ds_write2_b32 v50, v16, v32 offset0:128 offset1:160
	ds_write2_b32 v50, v17, v33 offset0:192 offset1:224
	s_waitcnt lgkmcnt(0)
	s_barrier
	global_load_dwordx2 v[52:53], v[56:57], off
	ds_read_b128 v[2:5], v47
	ds_read_b128 v[6:9], v47 offset:8192
	ds_read_b128 v[10:13], v47 offset:16384
	ds_read_b128 v[14:17], v47 offset:24576
	ds_read_b128 v[18:21], v47 offset:32768
	ds_read_b128 v[22:25], v47 offset:40960
	ds_read_b128 v[26:29], v47 offset:49152
	ds_read_b128 v[30:33], v47 offset:57344
	s_waitcnt lgkmcnt(7)
	v_pk_add_f32 v[4:5], v[4:5], 0 op_sel_hi:[1,0]
	v_pk_add_f32 v[2:3], v[2:3], 0 op_sel_hi:[1,0]
	s_waitcnt lgkmcnt(6)
	v_pk_add_f32 v[4:5], v[4:5], v[8:9]
	v_pk_add_f32 v[2:3], v[2:3], v[6:7]
	s_waitcnt lgkmcnt(5)
	v_pk_add_f32 v[4:5], v[4:5], v[12:13]
	v_pk_add_f32 v[2:3], v[2:3], v[10:11]
	s_waitcnt lgkmcnt(4)
	v_pk_add_f32 v[4:5], v[4:5], v[16:17]
	v_pk_add_f32 v[2:3], v[2:3], v[14:15]
	s_waitcnt lgkmcnt(3)
	v_pk_add_f32 v[4:5], v[4:5], v[20:21]
	v_pk_add_f32 v[2:3], v[2:3], v[18:19]
	s_waitcnt lgkmcnt(2)
	v_pk_add_f32 v[4:5], v[4:5], v[24:25]
	v_pk_add_f32 v[2:3], v[2:3], v[22:23]
	s_waitcnt lgkmcnt(1)
	v_pk_add_f32 v[4:5], v[4:5], v[28:29]
	v_pk_add_f32 v[2:3], v[2:3], v[26:27]
	s_waitcnt lgkmcnt(0)
	v_pk_add_f32 v[4:5], v[4:5], v[32:33]
	v_pk_add_f32 v[2:3], v[2:3], v[30:31]
	s_waitcnt vmcnt(0)
	v_lshlrev_b32_e32 v6, 16, v52
	v_and_b32_e32 v7, 0xffff0000, v52
	v_lshlrev_b32_e32 v8, 16, v53
	v_and_b32_e32 v9, 0xffff0000, v53
	v_pk_add_f32 v[4:5], v[4:5], v[8:9]
	v_pk_add_f32 v[6:7], v[2:3], v[6:7]
	v_mul_f32_e32 v3, v5, v5
	v_mul_f32_e32 v2, v7, v7
	v_fmac_f32_e32 v2, v6, v6
	v_fmac_f32_e32 v3, v4, v4
	v_add_f32_e32 v2, v2, v3
	ds_bpermute_b32 v3, v43, v2
	v_cvt_pk_bf16_f32 v6, v6, v7
	v_cvt_pk_bf16_f32 v7, v4, v5
	global_store_dwordx2 v[56:57], v[6:7], off
	s_waitcnt lgkmcnt(0)
	v_add_f32_e32 v2, v2, v3
	ds_bpermute_b32 v3, v44, v2
	s_waitcnt lgkmcnt(0)
	v_add_f32_e32 v2, v2, v3
	ds_bpermute_b32 v3, v45, v2
	s_waitcnt lgkmcnt(0)
	v_add_f32_e32 v2, v2, v3
	ds_bpermute_b32 v3, v46, v2
	s_and_saveexec_b64 s[0:1], vcc
	s_cbranch_execz .LBB0_1364
	s_waitcnt lgkmcnt(0)
	v_add_f32_e32 v2, v2, v3
	v_lshlrev_b32_e32 v3, 2, v51
	global_atomic_add_f32 v3, v2, s[8:9]
	s_branch .LBB0_1364

; template <class EpiS>
; DI void sample_gemm(LAS unsigned char* lds, const bf16_t* A, const bf16_t* Bt, int nN, int K, const EpiS& E) {
;     const int tid = threadIdx.x, lane = tid & 63, w = __builtin_amdgcn_readfirstlane(tid >> 6), r32 = lane & 31, h = lane >> 5;
;     const int nunits = 16 * nN, kw = K >> 3, nk = kw >> 4;
;     for (int un = (int)blockIdx.x; un < nunits; un += (int)gridDim.x) {
;         const int rb = un & 3, wc = (un >> 2) & 3, pn = un >> 4;
;         const bf16_t* ap = A + (size_t)(MP + rb * 32 + r32) * K + w * kw + h * 8;
;         const bf16_t* b0p = Bt + (size_t)(pn * 256 + wc * 32 + r32) * K + w * kw + h * 8;
;         const bf16_t* b1p = b0p + (size_t)128 * K;
;         f32x16 c0, c1;
; #pragma unroll
;         for (int r = 0; r < 16; ++r) { c0[r] = 0.f; c1[r] = 0.f; }
.LBB0_1435:
	s_cmpk_gt_i32 s2, 0x15f
	v_readfirstlane_b32 s0, v162
	s_cbranch_scc1 .LBB0_1440
	v_and_b32_e32 v155, 63, v162
	v_lshrrev_b32_e32 v156, 6, v162
	v_and_b32_e32 v156, 7, v156
	v_lshlrev_b32_e32 v156, 13, v156
	v_add_u32_e32 v156, 0x10000, v156
	v_lshrrev_b32_e32 v182, 3, v155
	v_and_b32_e32 v165, 31, v155
	v_sub_u32_e32 v182, v182, v165
	v_lshlrev_b32_e32 v182, 11, v182
	v_and_b32_e32 v165, 7, v155
	v_lshrrev_b32_e32 v183, 5, v155
	v_sub_u32_e32 v165, v165, v183
	v_lshl_add_u32 v182, v165, 4, v182
	v_ashrrev_i32_e32 v183, 31, v182
	v_lshrrev_b32_e32 v194, 4, v155
	v_and_b32_e32 v194, 3, v194
	v_and_b32_e32 v165, 7, v155
	v_xor_b32_e32 v194, v194, v165
	v_lshlrev_b32_e32 v194, 4, v194
	v_lshrrev_b32_e32 v165, 3, v155
	v_lshl_add_u32 v194, v165, 7, v194
	v_add_u32_e32 v194, v156, v194
	v_xor_b32_e32 v195, 64, v194
	v_and_b32_e32 v165, 31, v155
	v_lshl_add_u32 v156, v165, 7, v156
	v_lshrrev_b32_e32 v165, 1, v155
	v_and_b32_e32 v165, 7, v165
	v_lshrrev_b32_e32 v155, 5, v155
	v_add_u32_e32 v244, 0, v155
	v_xor_b32_e32 v244, v244, v165
	v_lshl_add_u32 v244, v244, 4, v156
	v_add_u32_e32 v245, 2, v155
	v_xor_b32_e32 v245, v245, v165
	v_lshl_add_u32 v245, v245, 4, v156
	v_add_u32_e32 v246, 4, v155
	v_xor_b32_e32 v246, v246, v165
	v_lshl_add_u32 v246, v246, 4, v156
	v_add_u32_e32 v193, 6, v155
	v_xor_b32_e32 v193, v193, v165
	v_lshl_add_u32 v193, v193, 4, v156
	s_mov_b32 s80, 0x4000
	s_mov_b32 s81, 0
	s_mov_b32 s82, 0xffff4000
	s_mov_b32 s83, -1
	v_and_b32_e32 v1, 1, v1
	v_lshlrev_b32_e32 v34, 4, v1
	v_mov_b32_e32 v35, 0
	s_lshr_b32 s0, s0, 6
	s_mov_b32 s5, 0
	v_lshl_add_u64 v[2:3], s[34:35], 0, v[34:35]
	s_lshl_b32 s4, s0, 8
	v_lshl_add_u64 v[36:37], v[2:3], 0, s[4:5]
	v_mbcnt_lo_u32_b32 v2, -1, 0
	v_lshl_add_u64 v[4:5], s[22:23], 0, v[34:35]
	v_mbcnt_hi_u32_b32 v2, -1, v2
	v_and_b32_e32 v42, 31, v162
	v_lshl_add_u64 v[38:39], v[4:5], 0, s[4:5]
	v_and_b32_e32 v4, 64, v2
	v_lshlrev_b32_e32 v1, 10, v1
	v_lshlrev_b32_e32 v6, 2, v42
	v_xor_b32_e32 v3, 8, v2
	v_add_u32_e32 v4, 64, v4
	v_add3_u32 v7, 0, v1, v6
	v_and_b32_e32 v1, 0x3f00, v164
	s_lshl_b32 s4, s0, 13
	v_cmp_lt_i32_e64 s[0:1], v3, v4
	v_add_u32_e32 v8, 0, v1
	v_and_b32_e32 v9, 0xf0, v164
	v_and_b32_e32 v1, 8, v162
	v_and_b32_e32 v6, 28, v163
	v_cndmask_b32_e64 v2, v2, v3, s[0:1]
	v_add_u32_e32 v44, s4, v7
	v_cmp_eq_u32_e32 vcc, 0, v1
	v_lshrrev_b32_e32 v1, 4, v162
	v_lshlrev_b32_e32 v43, 2, v2
	s_lshl_b32 s8, s2, 3
	s_lshl_b32 s9, s3, 3
	s_lshl_b32 s10, s2, 5
	s_lshl_b32 s11, s3, 5
	s_mov_b32 s12, 0x40000
	v_add_u32_e32 v45, v8, v9
	v_mov_b32_e32 v46, 0x358637bd
	s_mov_b32 s13, 0x800000
	v_lshlrev_b32_e32 v40, 1, v6
	v_add_u32_e32 v47, 0x800, v44
	v_add_u32_e32 v48, 0x1000, v44
	v_add_u32_e32 v49, 0x1800, v44
	s_mov_b32 s14, s2
	s_branch .LBB0_1438

; template <class EpiS>
; DI void sample_gemm(LAS unsigned char* lds, const bf16_t* A, const bf16_t* Bt, int nN, int K, const EpiS& E) {
;     ...
;     for (int un = (int)blockIdx.x; un < nunits; un += (int)gridDim.x) {
;         const int rb = un & 3, wc = (un >> 2) & 3, pn = un >> 4;
;         const bf16_t* ap = A + (size_t)(MP + rb * 32 + r32) * K + w * kw + h * 8;
;         const bf16_t* b0p = Bt + (size_t)(pn * 256 + wc * 32 + r32) * K + w * kw + h * 8;
;         const bf16_t* b1p = b0p + (size_t)128 * K;
;         f32x16 c0, c1;
; #pragma unroll
;         for (int r = 0; r < 16; ++r) { c0[r] = 0.f; c1[r] = 0.f; }
; #pragma unroll 8
;         for (int ks = 0; ks < nk; ++ks) {
;             const bf16x8 a = *(const bf16x8*)(ap + ks * 16), b0 = *(const bf16x8*)(b0p + ks * 16), b1 = *(const bf16x8*)(b1p + ks * 16);
;             c0 = __builtin_amdgcn_mfma_f32_32x32x16_bf16(a, b0, c0, 0, 0, 0);
;             c1 = __builtin_amdgcn_mfma_f32_32x32x16_bf16(a, b1, c1, 0, 0, 0);
;         }
;         __syncthreads();
.LBB0_1438:
	s_and_b32 s16, s10, 0x60
	s_bitset1_b32 s16, 15
	s_ashr_i32 s4, s14, 4
	s_waitcnt lgkmcnt(2)
	v_or_b32_e32 v3, s16, v42
	s_lshl_b32 s0, s4, 8
	s_and_b32 s15, s8, 0x60
	v_lshlrev_b32_e32 v34, 11, v3
	s_or_b32 s0, s0, s15
	v_lshl_add_u64 v[74:75], v[36:37], 0, v[34:35]
	v_or_b32_e32 v2, s0, v42
	v_ashrrev_i32_e32 v3, 31, v2
	v_lshlrev_b64 v[2:3], 11, v[2:3]
	v_lshl_add_u64 v[76:77], v[38:39], 0, v[2:3]
	s_waitcnt lgkmcnt(0)
	v_add_co_u32_e64 v78, s[0:1], s12, v76
	v_addc_co_u32_e64 v79, s[0:1], 0, v77, s[0:1]
	v_lshl_add_u64 v[158:159], v[74:75], 0, v[182:183]
	v_lshl_add_u64 v[160:161], v[76:77], 0, v[182:183]
	v_lshl_add_u64 v[180:181], v[78:79], 0, v[182:183]
	global_load_dwordx4 v[82:85], v[158:159], off
	v_lshl_add_u64 v[158:159], v[158:159], 0, s[80:81]
	global_load_dwordx4 v[86:89], v[158:159], off
	v_lshl_add_u64 v[158:159], v[158:159], 0, s[80:81]
	global_load_dwordx4 v[90:93], v[158:159], off
	v_lshl_add_u64 v[158:159], v[158:159], 0, s[80:81]
	global_load_dwordx4 v[94:97], v[158:159], off
	v_lshl_add_u64 v[158:159], v[158:159], 0, s[82:83]
	global_load_dwordx4 v[98:101], v[160:161], off
	v_lshl_add_u64 v[160:161], v[160:161], 0, s[80:81]
	global_load_dwordx4 v[102:105], v[160:161], off
	v_lshl_add_u64 v[160:161], v[160:161], 0, s[80:81]
	global_load_dwordx4 v[106:109], v[160:161], off
	v_lshl_add_u64 v[160:161], v[160:161], 0, s[80:81]
	global_load_dwordx4 v[110:113], v[160:161], off
	v_lshl_add_u64 v[160:161], v[160:161], 0, s[82:83]
	global_load_dwordx4 v[132:135], v[180:181], off
	v_lshl_add_u64 v[180:181], v[180:181], 0, s[80:81]
	global_load_dwordx4 v[136:139], v[180:181], off
	v_lshl_add_u64 v[180:181], v[180:181], 0, s[80:81]
	global_load_dwordx4 v[140:143], v[180:181], off
	v_lshl_add_u64 v[180:181], v[180:181], 0, s[80:81]
	global_load_dwordx4 v[144:147], v[180:181], off
	v_lshl_add_u64 v[180:181], v[180:181], 0, s[82:83]
	global_load_dwordx4 v[148:151], v[158:159], off offset:128
	v_lshl_add_u64 v[158:159], v[158:159], 0, s[80:81]
	global_load_dwordx4 v[166:169], v[158:159], off offset:128
	v_lshl_add_u64 v[158:159], v[158:159], 0, s[80:81]
	global_load_dwordx4 v[170:173], v[158:159], off offset:128
	v_lshl_add_u64 v[158:159], v[158:159], 0, s[80:81]
	global_load_dwordx4 v[174:177], v[158:159], off offset:128
	global_load_dwordx4 v[198:201], v[160:161], off offset:128
	v_lshl_add_u64 v[160:161], v[160:161], 0, s[80:81]
	global_load_dwordx4 v[202:205], v[160:161], off offset:128
	v_lshl_add_u64 v[160:161], v[160:161], 0, s[80:81]
	global_load_dwordx4 v[216:219], v[160:161], off offset:128
	v_lshl_add_u64 v[160:161], v[160:161], 0, s[80:81]
	global_load_dwordx4 v[220:223], v[160:161], off offset:128
	global_load_dwordx4 v[224:227], v[180:181], off offset:128
	v_lshl_add_u64 v[180:181], v[180:181], 0, s[80:81]
	global_load_dwordx4 v[228:231], v[180:181], off offset:128
	v_lshl_add_u64 v[180:181], v[180:181], 0, s[80:81]
	global_load_dwordx4 v[232:235], v[180:181], off offset:128
	v_lshl_add_u64 v[180:181], v[180:181], 0, s[80:81]
	global_load_dwordx4 v[236:239], v[180:181], off offset:128
	s_waitcnt vmcnt(16)
	ds_write_b128 v194, v[82:85]
	ds_write_b128 v195, v[86:89] offset:1024
	ds_write_b128 v194, v[90:93] offset:2048
	ds_write_b128 v195, v[94:97] offset:3072
	ds_write_b128 v194, v[98:101] offset:4096
	ds_write_b128 v195, v[102:105] offset:5120
	ds_write_b128 v194, v[106:109] offset:6144
	ds_write_b128 v195, v[110:113] offset:7168
	ds_read_b128 v[82:85], v244
	ds_read_b128 v[86:89], v245
	ds_read_b128 v[90:93], v246
	ds_read_b128 v[94:97], v193
	ds_read_b128 v[98:101], v244 offset:4096
	ds_read_b128 v[102:105], v245 offset:4096
	ds_read_b128 v[106:109], v246 offset:4096
	ds_read_b128 v[110:113], v193 offset:4096
	s_waitcnt lgkmcnt(0)
	v_mfma_f32_32x32x16_bf16 v[2:17], v[82:85], v[98:101], 0
	v_mfma_f32_32x32x16_bf16 v[2:17], v[86:89], v[102:105], v[2:17]
	v_mfma_f32_32x32x16_bf16 v[2:17], v[90:93], v[106:109], v[2:17]
	v_mfma_f32_32x32x16_bf16 v[2:17], v[94:97], v[110:113], v[2:17]
	s_waitcnt vmcnt(12)
	ds_write_b128 v194, v[132:135] offset:4096
	ds_write_b128 v195, v[136:139] offset:5120
	ds_write_b128 v194, v[140:143] offset:6144
	ds_write_b128 v195, v[144:147] offset:7168
	ds_read_b128 v[132:135], v244 offset:4096
	ds_read_b128 v[136:139], v245 offset:4096
	ds_read_b128 v[140:143], v246 offset:4096
	ds_read_b128 v[144:147], v193 offset:4096
	s_waitcnt lgkmcnt(0)
	v_mfma_f32_32x32x16_bf16 v[18:33], v[82:85], v[132:135], 0
	v_mfma_f32_32x32x16_bf16 v[18:33], v[86:89], v[136:139], v[18:33]
	v_mfma_f32_32x32x16_bf16 v[18:33], v[90:93], v[140:143], v[18:33]
	v_mfma_f32_32x32x16_bf16 v[18:33], v[94:97], v[144:147], v[18:33]
	s_waitcnt vmcnt(4)
	ds_write_b128 v194, v[148:151]
	ds_write_b128 v195, v[166:169] offset:1024
	ds_write_b128 v194, v[170:173] offset:2048
	ds_write_b128 v195, v[174:177] offset:3072
	ds_write_b128 v194, v[198:201] offset:4096
	ds_write_b128 v195, v[202:205] offset:5120
	ds_write_b128 v194, v[216:219] offset:6144
	ds_write_b128 v195, v[220:223] offset:7168
	ds_read_b128 v[148:151], v244
	ds_read_b128 v[166:169], v245
	ds_read_b128 v[170:173], v246
	ds_read_b128 v[174:177], v193
	ds_read_b128 v[198:201], v244 offset:4096
	ds_read_b128 v[202:205], v245 offset:4096
	ds_read_b128 v[216:219], v246 offset:4096
	ds_read_b128 v[220:223], v193 offset:4096
	s_waitcnt lgkmcnt(0)
	v_mfma_f32_32x32x16_bf16 v[2:17], v[148:151], v[198:201], v[2:17]
	v_mfma_f32_32x32x16_bf16 v[2:17], v[166:169], v[202:205], v[2:17]
	v_mfma_f32_32x32x16_bf16 v[2:17], v[170:173], v[216:219], v[2:17]
	v_mfma_f32_32x32x16_bf16 v[2:17], v[174:177], v[220:223], v[2:17]
	s_waitcnt vmcnt(0)
	ds_write_b128 v194, v[224:227] offset:4096
	ds_write_b128 v195, v[228:231] offset:5120
	ds_write_b128 v194, v[232:235] offset:6144
	ds_write_b128 v195, v[236:239] offset:7168
	ds_read_b128 v[224:227], v244 offset:4096
	ds_read_b128 v[228:231], v245 offset:4096
	ds_read_b128 v[232:235], v246 offset:4096
	ds_read_b128 v[236:239], v193 offset:4096
	s_waitcnt lgkmcnt(0)
	v_mfma_f32_32x32x16_bf16 v[18:33], v[148:151], v[224:227], v[18:33]
	v_mfma_f32_32x32x16_bf16 v[18:33], v[166:169], v[228:231], v[18:33]
	v_mfma_f32_32x32x16_bf16 v[18:33], v[170:173], v[232:235], v[18:33]
	v_mfma_f32_32x32x16_bf16 v[18:33], v[174:177], v[236:239], v[18:33]
	s_barrier
; #define LAS __attribute__((address_space(3)))
; DI float sigmoidf_(float x) { return __builtin_amdgcn_rcpf(1.0f + __expf(-x)); }
; DI float row_rstd(const float* SS, int row) { return rsqrtf(SS[row] * (1.0f / 1024.0f) + 1e-6f); }
; DI f32x4 shx8(const f32x4 v) { f32x4 o; o[0] = __shfl_xor(v[0], 8); o[1] = __shfl_xor(v[1], 8); o[2] = __shfl_xor(v[2], 8); o[3] = __shfl_xor(v[3], 8); return o; }
; DI u32x2 pk4(const f32x4 a) { return (u32x2){pk2(a[0], a[1]), pk2(a[2], a[3])}; }
;     DI void operator()(const f32x4 v, int row, int pn, int wc, int bj, int cl) const {
;         const float rs = row_rstd(SS, row);
;         const f32x4 o = shx8(v);
;         if (bj == 0) {
;             f32x4 hv;
; #pragma unroll
;             for (int i = 0; i < 4; ++i) { const float g0 = v[i] * rs; hv[i] = g0 * sigmoidf_(g0) * (o[i] * rs); }
;             *(u32x2*)(HID + (size_t)row * FH + pn * 128 + wc * 32 + cl) = pk4(hv);
;         }
; template <class EpiS>
; DI void sample_gemm(LAS unsigned char* lds, const bf16_t* A, const bf16_t* Bt, int nN, int K, const EpiS& E) {
;     ...
;         __syncthreads();
;         LAS float* part = (LAS float*)(lds + w * 8192);
; #pragma unroll
;         for (int r = 0; r < 16; ++r) { const int row = (r & 3) + 8 * (r >> 2) + 4 * h; part[row * 64 + r32] = c0[r]; part[row * 64 + 32 + r32] = c1[r]; }
;         __syncthreads();
;         f32x4 v = (f32x4){0.f, 0.f, 0.f, 0.f};
; #pragma unroll
;         for (int ww = 0; ww < 8; ++ww) v += *(const LAS f32x4*)(lds + ww * 8192 + (tid >> 4) * 256 + (tid & 15) * 16);
;         E(v, MP + rb * 32 + (tid >> 4), pn, wc, (tid >> 3) & 1, 4 * (tid & 7));
	s_nop 11
	ds_write2_b32 v44, v2, v18 offset1:32
	ds_write2_b32 v44, v3, v19 offset0:64 offset1:96
	ds_write2_b32 v44, v4, v20 offset0:128 offset1:160
	ds_write2_b32 v44, v5, v21 offset0:192 offset1:224
	ds_write2_b32 v47, v6, v22 offset1:32
	ds_write2_b32 v47, v7, v23 offset0:64 offset1:96
	ds_write2_b32 v47, v8, v24 offset0:128 offset1:160
	ds_write2_b32 v47, v9, v25 offset0:192 offset1:224
	ds_write2_b32 v48, v10, v26 offset1:32
	ds_write2_b32 v48, v11, v27 offset0:64 offset1:96
	ds_write2_b32 v48, v12, v28 offset0:128 offset1:160
	ds_write2_b32 v48, v13, v29 offset0:192 offset1:224
	ds_write2_b32 v49, v14, v30 offset1:32
	ds_write2_b32 v49, v15, v31 offset0:64 offset1:96
	ds_write2_b32 v49, v16, v32 offset0:128 offset1:160
	ds_write2_b32 v49, v17, v33 offset0:192 offset1:224
	s_waitcnt lgkmcnt(0)
	s_barrier
	ds_read_b128 v[2:5], v45
	ds_read_b128 v[6:9], v45 offset:8192
	ds_read_b128 v[10:13], v45 offset:16384
	ds_read_b128 v[14:17], v45 offset:24576
	ds_read_b128 v[18:21], v45 offset:32768
	ds_read_b128 v[22:25], v45 offset:40960
	ds_read_b128 v[26:29], v45 offset:49152
	ds_read_b128 v[30:33], v45 offset:57344
	s_waitcnt lgkmcnt(7)
	v_pk_add_f32 v[4:5], v[4:5], 0 op_sel_hi:[1,0]
	v_pk_add_f32 v[2:3], v[2:3], 0 op_sel_hi:[1,0]
	s_waitcnt lgkmcnt(6)
	v_pk_add_f32 v[4:5], v[4:5], v[8:9]
	v_pk_add_f32 v[2:3], v[2:3], v[6:7]
	s_waitcnt lgkmcnt(5)
	v_pk_add_f32 v[4:5], v[4:5], v[12:13]
	v_pk_add_f32 v[2:3], v[2:3], v[10:11]
	s_waitcnt lgkmcnt(4)
	v_pk_add_f32 v[4:5], v[4:5], v[16:17]
	v_pk_add_f32 v[2:3], v[2:3], v[14:15]
	s_waitcnt lgkmcnt(3)
	v_pk_add_f32 v[4:5], v[4:5], v[20:21]
	v_pk_add_f32 v[2:3], v[2:3], v[18:19]
	s_waitcnt lgkmcnt(2)
	v_pk_add_f32 v[4:5], v[4:5], v[24:25]
	v_pk_add_f32 v[2:3], v[2:3], v[22:23]
	s_waitcnt lgkmcnt(1)
	v_pk_add_f32 v[4:5], v[4:5], v[28:29]
	v_pk_add_f32 v[2:3], v[2:3], v[26:27]
	s_waitcnt lgkmcnt(0)
	v_pk_add_f32 v[6:7], v[4:5], v[32:33]
	v_pk_add_f32 v[8:9], v[2:3], v[30:31]
	ds_bpermute_b32 v2, v43, v8
	ds_bpermute_b32 v3, v43, v9
	ds_bpermute_b32 v4, v43, v6
	ds_bpermute_b32 v5, v43, v7
	s_and_saveexec_b64 s[6:7], vcc
	s_cbranch_execz .LBB0_1437
	v_add_u32_e32 v10, s16, v1
	v_lshlrev_b32_e32 v11, 2, v10
	global_load_dword v11, v11, s[20:21]
	v_mul_u32_u24_e32 v10, 0xb00, v10
	v_lshlrev_b32_e32 v34, 1, v10
	s_lshl_b32 s16, s4, 7
	s_ashr_i32 s17, s16, 31
	s_lshl_b32 s4, s15, 1
	v_mov_b32_e32 v41, v35
	s_waitcnt vmcnt(0)
	v_fmamk_f32 v10, v11, 0x3a800000, v46
	v_mul_f32_e32 v11, 0x4b800000, v10
	v_cmp_gt_f32_e64 s[0:1], s13, v10
	s_nop 1
	v_cndmask_b32_e64 v10, v10, v11, s[0:1]
	v_rsq_f32_e32 v12, v10
	v_lshl_add_u64 v[10:11], s[24:25], 0, v[34:35]
	v_lshl_add_u64 v[10:11], s[16:17], 1, v[10:11]
	v_lshl_add_u64 v[10:11], v[10:11], 0, s[4:5]
	v_mul_f32_e32 v13, 0x45800000, v12
	v_cndmask_b32_e64 v12, v12, v13, s[0:1]
	v_pk_mul_f32 v[8:9], v[8:9], v[12:13] op_sel_hi:[1,0]
	v_pk_mul_f32 v[6:7], v[6:7], v[12:13] op_sel_hi:[1,0]
	v_mul_f32_e32 v13, 0xbfb8aa3b, v8
	v_mul_f32_e32 v14, 0xbfb8aa3b, v9
	v_mul_f32_e32 v15, 0xbfb8aa3b, v6
	v_mul_f32_e32 v16, 0xbfb8aa3b, v7
	v_exp_f32_e32 v13, v13
	v_exp_f32_e32 v14, v14
	v_exp_f32_e32 v15, v15
	v_exp_f32_e32 v16, v16
	v_add_f32_e32 v13, 1.0, v13
	v_add_f32_e32 v17, 1.0, v14
	v_add_f32_e32 v18, 1.0, v15
	v_add_f32_e32 v19, 1.0, v16
	v_rcp_f32_e32 v14, v13
	v_rcp_f32_e32 v15, v17
	v_rcp_f32_e32 v16, v18
	v_rcp_f32_e32 v17, v19
	s_waitcnt lgkmcnt(2)
	v_pk_mul_f32 v[2:3], v[12:13], v[2:3] op_sel_hi:[0,1]
	s_waitcnt lgkmcnt(0)
	v_pk_mul_f32 v[4:5], v[12:13], v[4:5] op_sel_hi:[0,1]
	v_pk_mul_f32 v[8:9], v[8:9], v[14:15]
	v_pk_mul_f32 v[6:7], v[6:7], v[16:17]
	v_pk_mul_f32 v[2:3], v[2:3], v[8:9]
	v_pk_mul_f32 v[4:5], v[4:5], v[6:7]
	v_cvt_pk_bf16_f32 v2, v2, v3
	v_cvt_pk_bf16_f32 v3, v4, v5
	v_lshl_add_u64 v[4:5], v[10:11], 0, v[40:41]
	global_store_dwordx2 v[4:5], v[2:3], off
	s_branch .LBB0_1437
